# s_barrier moved 4 MFMAs up inside each GEMM MMA block, tail at setprio 2
# speedup vs baseline: 1.0055x; 1.0013x over previous
.LBB0_323:
	ds_read_b128 v[96:99], v209
	ds_read_b128 v[100:103], v209 offset:1024
	ds_read_b128 v[120:123], v209 offset:2048
	ds_read_b128 v[124:127], v209 offset:3072
	ds_read_b128 v[144:147], v210
	ds_read_b128 v[148:151], v210 offset:1024
	ds_read_b128 v[152:155], v210 offset:2048
	ds_read_b128 v[156:159], v210 offset:3072
	s_add_u32 s8, s6, 0xfffc0080
	s_addc_u32 s9, s7, -1
	s_cmp_eq_u32 s78, 12
	s_cselect_b32 s51, s18, s9
	s_cselect_b32 s50, s43, s8
	s_cselect_b32 s9, s45, s57
	s_cselect_b32 s8, s55, s56
	v_lshl_add_u64 v[206:207], s[6:7], 0, v[170:171]
	s_add_i32 m0, s17, 0xc000
	ds_read_b128 v[178:181], v211
	ds_read_b128 v[182:185], v211 offset:1024
	ds_read_b128 v[186:189], v211 offset:2048
	ds_read_b128 v[190:193], v211 offset:3072
	ds_read_b128 v[194:197], v211 offset:4096
	ds_read_b128 v[198:201], v211 offset:5120
	ds_read_b128 v[202:205], v211 offset:6144
	ds_read_b128 v[218:221], v211 offset:7168
	global_load_lds_dwordx4 v[206:207], off
	v_lshl_add_u64 v[206:207], s[6:7], 0, v[172:173]
	s_add_i32 m0, s17, 0xe000
	s_nop 0
	global_load_lds_dwordx4 v[206:207], off
	s_waitcnt vmcnt(8)
	s_waitcnt lgkmcnt(0)
	s_barrier
	s_setprio 1
	s_waitcnt lgkmcnt(0)
	v_mfma_f32_16x16x32_bf16 v[140:143], v[96:99], v[178:181], v[140:143]
	v_mfma_f32_16x16x32_bf16 v[136:139], v[120:123], v[178:181], v[136:139]
	v_mfma_f32_16x16x32_bf16 v[116:119], v[96:99], v[186:189], v[116:119]
	v_mfma_f32_16x16x32_bf16 v[112:115], v[120:123], v[186:189], v[112:115]
	v_mfma_f32_16x16x32_bf16 v[92:95], v[96:99], v[194:197], v[92:95]
	v_mfma_f32_16x16x32_bf16 v[88:91], v[120:123], v[194:197], v[88:91]
	v_mfma_f32_16x16x32_bf16 v[76:79], v[96:99], v[202:205], v[76:79]
	v_mfma_f32_16x16x32_bf16 v[72:75], v[120:123], v[202:205], v[72:75]
	v_mfma_f32_16x16x32_bf16 v[140:143], v[100:103], v[182:185], v[140:143]
	v_mfma_f32_16x16x32_bf16 v[136:139], v[124:127], v[182:185], v[136:139]
	v_mfma_f32_16x16x32_bf16 v[116:119], v[100:103], v[190:193], v[116:119]
	v_mfma_f32_16x16x32_bf16 v[112:115], v[124:127], v[190:193], v[112:115]
	v_mfma_f32_16x16x32_bf16 v[92:95], v[100:103], v[198:201], v[92:95]
	v_mfma_f32_16x16x32_bf16 v[88:91], v[124:127], v[198:201], v[88:91]
	v_mfma_f32_16x16x32_bf16 v[76:79], v[100:103], v[218:221], v[76:79]
	v_mfma_f32_16x16x32_bf16 v[72:75], v[124:127], v[218:221], v[72:75]
	s_setprio 0
	s_setprio 1
	v_mfma_f32_16x16x32_bf16 v[132:135], v[144:147], v[178:181], v[132:135]
	v_mfma_f32_16x16x32_bf16 v[128:131], v[152:155], v[178:181], v[128:131]
	v_mfma_f32_16x16x32_bf16 v[108:111], v[144:147], v[186:189], v[108:111]
	v_mfma_f32_16x16x32_bf16 v[104:107], v[152:155], v[186:189], v[104:107]
	v_mfma_f32_16x16x32_bf16 v[84:87], v[144:147], v[194:197], v[84:87]
	v_mfma_f32_16x16x32_bf16 v[80:83], v[152:155], v[194:197], v[80:83]
	v_mfma_f32_16x16x32_bf16 v[68:71], v[144:147], v[202:205], v[68:71]
	v_mfma_f32_16x16x32_bf16 v[64:67], v[152:155], v[202:205], v[64:67]
	v_mfma_f32_16x16x32_bf16 v[132:135], v[148:151], v[182:185], v[132:135]
	v_mfma_f32_16x16x32_bf16 v[128:131], v[156:159], v[182:185], v[128:131]
	v_mfma_f32_16x16x32_bf16 v[108:111], v[148:151], v[190:193], v[108:111]
	v_mfma_f32_16x16x32_bf16 v[104:107], v[156:159], v[190:193], v[104:107]
	s_setprio 2
	s_barrier
	v_mfma_f32_16x16x32_bf16 v[84:87], v[148:151], v[198:201], v[84:87]
	v_mfma_f32_16x16x32_bf16 v[80:83], v[156:159], v[198:201], v[80:83]
	v_mfma_f32_16x16x32_bf16 v[68:71], v[148:151], v[218:221], v[68:71]
	v_mfma_f32_16x16x32_bf16 v[64:67], v[156:159], v[218:221], v[64:67]
	s_setprio 0
	s_add_i32 s79, s73, s61
	v_lshl_add_u64 v[206:207], s[8:9], 0, v[162:163]
	s_mov_b32 m0, s79
	ds_read_b128 v[178:181], v211 offset:16384
	ds_read_b128 v[182:185], v211 offset:17408
	ds_read_b128 v[186:189], v211 offset:18432
	ds_read_b128 v[190:193], v211 offset:19456
	ds_read_b128 v[194:197], v211 offset:20480
	ds_read_b128 v[198:201], v211 offset:21504
	ds_read_b128 v[202:205], v211 offset:22528
	ds_read_b128 v[218:221], v211 offset:23552
	global_load_lds_dwordx4 v[206:207], off
	s_add_i32 m0, s79, 0x2000
	s_add_u32 s80, s8, 0x40000
	v_lshl_add_u64 v[222:223], s[8:9], 0, v[166:167]
	s_addc_u32 s81, s9, 0
	s_add_i32 s79, s74, s61
	global_load_lds_dwordx4 v[222:223], off
	v_lshl_add_u64 v[224:225], s[80:81], 0, v[162:163]
	s_mov_b32 m0, s79
	v_lshl_add_u64 v[226:227], s[50:51], 0, v[164:165]
	global_load_lds_dwordx4 v[224:225], off
	v_lshl_add_u64 v[224:225], s[80:81], 0, v[166:167]
	s_add_i32 m0, s79, 0x2000
	s_nop 0
	global_load_lds_dwordx4 v[224:225], off
	v_lshl_add_u64 v[224:225], s[50:51], 0, v[160:161]
	s_mov_b32 m0, s17
	s_nop 0
	global_load_lds_dwordx4 v[224:225], off
	s_mov_b32 m0, s62
	s_nop 0
	global_load_lds_dwordx4 v[226:227], off
	s_waitcnt vmcnt(8)
	s_waitcnt lgkmcnt(0)
	s_barrier
	s_setprio 1
	s_waitcnt lgkmcnt(0)
	v_mfma_f32_16x16x32_bf16 v[60:63], v[96:99], v[178:181], v[60:63]
	v_mfma_f32_16x16x32_bf16 v[56:59], v[120:123], v[178:181], v[56:59]
	v_mfma_f32_16x16x32_bf16 v[44:47], v[96:99], v[186:189], v[44:47]
	v_mfma_f32_16x16x32_bf16 v[40:43], v[120:123], v[186:189], v[40:43]
	v_mfma_f32_16x16x32_bf16 v[28:31], v[96:99], v[194:197], v[28:31]
	v_mfma_f32_16x16x32_bf16 v[24:27], v[120:123], v[194:197], v[24:27]
	v_mfma_f32_16x16x32_bf16 v[12:15], v[96:99], v[202:205], v[12:15]
	v_mfma_f32_16x16x32_bf16 v[8:11], v[120:123], v[202:205], v[8:11]
	v_mfma_f32_16x16x32_bf16 v[60:63], v[100:103], v[182:185], v[60:63]
	v_mfma_f32_16x16x32_bf16 v[56:59], v[124:127], v[182:185], v[56:59]
	v_mfma_f32_16x16x32_bf16 v[44:47], v[100:103], v[190:193], v[44:47]
	v_mfma_f32_16x16x32_bf16 v[40:43], v[124:127], v[190:193], v[40:43]
	v_mfma_f32_16x16x32_bf16 v[28:31], v[100:103], v[198:201], v[28:31]
	v_mfma_f32_16x16x32_bf16 v[24:27], v[124:127], v[198:201], v[24:27]
	v_mfma_f32_16x16x32_bf16 v[12:15], v[100:103], v[218:221], v[12:15]
	v_mfma_f32_16x16x32_bf16 v[8:11], v[124:127], v[218:221], v[8:11]
	s_setprio 0
	s_setprio 1
	v_mfma_f32_16x16x32_bf16 v[52:55], v[144:147], v[178:181], v[52:55]
	v_mfma_f32_16x16x32_bf16 v[48:51], v[152:155], v[178:181], v[48:51]
	v_mfma_f32_16x16x32_bf16 v[36:39], v[144:147], v[186:189], v[36:39]
	v_mfma_f32_16x16x32_bf16 v[32:35], v[152:155], v[186:189], v[32:35]
	v_mfma_f32_16x16x32_bf16 v[20:23], v[144:147], v[194:197], v[20:23]
	v_mfma_f32_16x16x32_bf16 v[16:19], v[152:155], v[194:197], v[16:19]
	v_mfma_f32_16x16x32_bf16 v[4:7], v[144:147], v[202:205], v[4:7]
	v_mfma_f32_16x16x32_bf16 v[0:3], v[152:155], v[202:205], v[0:3]
	v_mfma_f32_16x16x32_bf16 v[52:55], v[148:151], v[182:185], v[52:55]
	v_mfma_f32_16x16x32_bf16 v[48:51], v[156:159], v[182:185], v[48:51]
	v_mfma_f32_16x16x32_bf16 v[36:39], v[148:151], v[190:193], v[36:39]
	v_mfma_f32_16x16x32_bf16 v[32:35], v[156:159], v[190:193], v[32:35]
	s_setprio 2
	s_barrier
	v_mfma_f32_16x16x32_bf16 v[20:23], v[148:151], v[198:201], v[20:23]
	v_mfma_f32_16x16x32_bf16 v[16:19], v[156:159], v[198:201], v[16:19]
	v_mfma_f32_16x16x32_bf16 v[4:7], v[148:151], v[218:221], v[4:7]
	v_mfma_f32_16x16x32_bf16 v[0:3], v[156:159], v[218:221], v[0:3]
	s_setprio 0
	s_add_i32 s79, 0, 0x18000
	s_add_i32 s80, 0, 0x1c000
	v_add_u32_e32 v124, s79, v208
	v_add_u32_e32 v156, s80, v208
	ds_read_b128 v[96:99], v124
	ds_read_b128 v[100:103], v124 offset:1024
	ds_read_b128 v[120:123], v124 offset:2048
	ds_read_b128 v[124:127], v124 offset:3072
	ds_read_b128 v[144:147], v156
	ds_read_b128 v[148:151], v156 offset:1024
	ds_read_b128 v[152:155], v156 offset:2048
	ds_read_b128 v[156:159], v156 offset:3072
	s_add_u32 s50, s50, 0x40000
	s_addc_u32 s51, s51, 0
	s_mov_b32 m0, s63
	v_lshl_add_u64 v[228:229], s[50:51], 0, v[160:161]
	ds_read_b128 v[178:181], v211 offset:32768
	ds_read_b128 v[182:185], v211 offset:33792
	ds_read_b128 v[186:189], v211 offset:34816
	ds_read_b128 v[190:193], v211 offset:35840
	ds_read_b128 v[194:197], v211 offset:36864
	ds_read_b128 v[198:201], v211 offset:37888
	ds_read_b128 v[202:205], v211 offset:38912
	ds_read_b128 v[218:221], v211 offset:39936
	global_load_lds_dwordx4 v[228:229], off
	v_lshl_add_u64 v[228:229], s[50:51], 0, v[164:165]
	s_mov_b32 m0, s64
	s_nop 0
	global_load_lds_dwordx4 v[228:229], off
	s_waitcnt vmcnt(8)
	s_waitcnt lgkmcnt(0)
	s_barrier
	s_setprio 1
	s_waitcnt lgkmcnt(0)
	v_mfma_f32_16x16x32_bf16 v[140:143], v[96:99], v[178:181], v[140:143]
	v_mfma_f32_16x16x32_bf16 v[136:139], v[120:123], v[178:181], v[136:139]
	v_mfma_f32_16x16x32_bf16 v[116:119], v[96:99], v[186:189], v[116:119]
	v_mfma_f32_16x16x32_bf16 v[112:115], v[120:123], v[186:189], v[112:115]
	v_mfma_f32_16x16x32_bf16 v[92:95], v[96:99], v[194:197], v[92:95]
	v_mfma_f32_16x16x32_bf16 v[88:91], v[120:123], v[194:197], v[88:91]
	v_mfma_f32_16x16x32_bf16 v[76:79], v[96:99], v[202:205], v[76:79]
	v_mfma_f32_16x16x32_bf16 v[72:75], v[120:123], v[202:205], v[72:75]
	v_mfma_f32_16x16x32_bf16 v[140:143], v[100:103], v[182:185], v[140:143]
	v_mfma_f32_16x16x32_bf16 v[136:139], v[124:127], v[182:185], v[136:139]
	v_mfma_f32_16x16x32_bf16 v[116:119], v[100:103], v[190:193], v[116:119]
	v_mfma_f32_16x16x32_bf16 v[112:115], v[124:127], v[190:193], v[112:115]
	v_mfma_f32_16x16x32_bf16 v[92:95], v[100:103], v[198:201], v[92:95]
	v_mfma_f32_16x16x32_bf16 v[88:91], v[124:127], v[198:201], v[88:91]
	v_mfma_f32_16x16x32_bf16 v[76:79], v[100:103], v[218:221], v[76:79]
	v_mfma_f32_16x16x32_bf16 v[72:75], v[124:127], v[218:221], v[72:75]
	s_setprio 0
	s_setprio 1
	v_mfma_f32_16x16x32_bf16 v[132:135], v[144:147], v[178:181], v[132:135]
	v_mfma_f32_16x16x32_bf16 v[128:131], v[152:155], v[178:181], v[128:131]
	v_mfma_f32_16x16x32_bf16 v[108:111], v[144:147], v[186:189], v[108:111]
	v_mfma_f32_16x16x32_bf16 v[104:107], v[152:155], v[186:189], v[104:107]
	v_mfma_f32_16x16x32_bf16 v[84:87], v[144:147], v[194:197], v[84:87]
	v_mfma_f32_16x16x32_bf16 v[80:83], v[152:155], v[194:197], v[80:83]
	v_mfma_f32_16x16x32_bf16 v[68:71], v[144:147], v[202:205], v[68:71]
	v_mfma_f32_16x16x32_bf16 v[64:67], v[152:155], v[202:205], v[64:67]
	v_mfma_f32_16x16x32_bf16 v[132:135], v[148:151], v[182:185], v[132:135]
	v_mfma_f32_16x16x32_bf16 v[128:131], v[156:159], v[182:185], v[128:131]
	v_mfma_f32_16x16x32_bf16 v[108:111], v[148:151], v[190:193], v[108:111]
	v_mfma_f32_16x16x32_bf16 v[104:107], v[156:159], v[190:193], v[104:107]
	s_setprio 2
	s_barrier
	v_mfma_f32_16x16x32_bf16 v[84:87], v[148:151], v[198:201], v[84:87]
	v_mfma_f32_16x16x32_bf16 v[80:83], v[156:159], v[198:201], v[80:83]
	v_mfma_f32_16x16x32_bf16 v[68:71], v[148:151], v[218:221], v[68:71]
	v_mfma_f32_16x16x32_bf16 v[64:67], v[156:159], v[218:221], v[64:67]
	s_setprio 0
	s_add_i32 s50, s79, s61
	v_lshl_add_u64 v[206:207], v[206:207], 0, s[36:37]
	s_mov_b32 m0, s50
	ds_read_b128 v[178:181], v211 offset:49152
	ds_read_b128 v[182:185], v211 offset:50176
	ds_read_b128 v[186:189], v211 offset:51200
	ds_read_b128 v[190:193], v211 offset:52224
	ds_read_b128 v[194:197], v211 offset:53248
	ds_read_b128 v[198:201], v211 offset:54272
	ds_read_b128 v[202:205], v211 offset:55296
	ds_read_b128 v[218:221], v211 offset:56320
	global_load_lds_dwordx4 v[206:207], off
	s_add_i32 m0, s50, 0x2000
	s_add_u32 s8, s8, 0x40080
	v_lshl_add_u64 v[206:207], v[222:223], 0, s[36:37]
	s_addc_u32 s9, s9, 0
	s_add_i32 s50, s80, s61
	global_load_lds_dwordx4 v[206:207], off
	v_lshl_add_u64 v[206:207], s[8:9], 0, v[162:163]
	s_mov_b32 m0, s50
	s_nop 0
	global_load_lds_dwordx4 v[206:207], off
	v_lshl_add_u64 v[206:207], s[8:9], 0, v[166:167]
	s_add_i32 m0, s50, 0x2000
	s_nop 0
	global_load_lds_dwordx4 v[206:207], off
	v_lshl_add_u64 v[206:207], v[224:225], 0, s[36:37]
	s_mov_b32 m0, s68
	s_nop 0
	global_load_lds_dwordx4 v[206:207], off
	v_lshl_add_u64 v[206:207], v[226:227], 0, s[36:37]
	s_mov_b32 m0, s69
	s_nop 0
	global_load_lds_dwordx4 v[206:207], off
	s_waitcnt vmcnt(8)
	s_waitcnt lgkmcnt(0)
	s_barrier
	s_setprio 1
	s_waitcnt lgkmcnt(0)
	v_mfma_f32_16x16x32_bf16 v[60:63], v[96:99], v[178:181], v[60:63]
	v_mfma_f32_16x16x32_bf16 v[56:59], v[120:123], v[178:181], v[56:59]
	v_mfma_f32_16x16x32_bf16 v[44:47], v[96:99], v[186:189], v[44:47]
	v_mfma_f32_16x16x32_bf16 v[40:43], v[120:123], v[186:189], v[40:43]
	v_mfma_f32_16x16x32_bf16 v[28:31], v[96:99], v[194:197], v[28:31]
	v_mfma_f32_16x16x32_bf16 v[24:27], v[120:123], v[194:197], v[24:27]
	v_mfma_f32_16x16x32_bf16 v[12:15], v[96:99], v[202:205], v[12:15]
	v_mfma_f32_16x16x32_bf16 v[8:11], v[120:123], v[202:205], v[8:11]
	v_mfma_f32_16x16x32_bf16 v[60:63], v[100:103], v[182:185], v[60:63]
	v_mfma_f32_16x16x32_bf16 v[56:59], v[124:127], v[182:185], v[56:59]
	v_mfma_f32_16x16x32_bf16 v[44:47], v[100:103], v[190:193], v[44:47]
	v_mfma_f32_16x16x32_bf16 v[40:43], v[124:127], v[190:193], v[40:43]
	v_mfma_f32_16x16x32_bf16 v[28:31], v[100:103], v[198:201], v[28:31]
	v_mfma_f32_16x16x32_bf16 v[24:27], v[124:127], v[198:201], v[24:27]
	v_mfma_f32_16x16x32_bf16 v[12:15], v[100:103], v[218:221], v[12:15]
	v_mfma_f32_16x16x32_bf16 v[8:11], v[124:127], v[218:221], v[8:11]
	s_setprio 0
	s_setprio 1
	v_mfma_f32_16x16x32_bf16 v[52:55], v[144:147], v[178:181], v[52:55]
	v_mfma_f32_16x16x32_bf16 v[48:51], v[152:155], v[178:181], v[48:51]
	v_mfma_f32_16x16x32_bf16 v[36:39], v[144:147], v[186:189], v[36:39]
	v_mfma_f32_16x16x32_bf16 v[32:35], v[152:155], v[186:189], v[32:35]
	v_mfma_f32_16x16x32_bf16 v[20:23], v[144:147], v[194:197], v[20:23]
	v_mfma_f32_16x16x32_bf16 v[16:19], v[152:155], v[194:197], v[16:19]
	v_mfma_f32_16x16x32_bf16 v[4:7], v[144:147], v[202:205], v[4:7]
	v_mfma_f32_16x16x32_bf16 v[0:3], v[152:155], v[202:205], v[0:3]
	v_mfma_f32_16x16x32_bf16 v[52:55], v[148:151], v[182:185], v[52:55]
	v_mfma_f32_16x16x32_bf16 v[48:51], v[156:159], v[182:185], v[48:51]
	v_mfma_f32_16x16x32_bf16 v[36:39], v[148:151], v[190:193], v[36:39]
	v_mfma_f32_16x16x32_bf16 v[32:35], v[156:159], v[190:193], v[32:35]
	s_setprio 2
	s_barrier
	v_mfma_f32_16x16x32_bf16 v[20:23], v[148:151], v[198:201], v[20:23]
	v_mfma_f32_16x16x32_bf16 v[16:19], v[156:159], v[198:201], v[16:19]
	v_mfma_f32_16x16x32_bf16 v[4:7], v[148:151], v[218:221], v[4:7]
	v_mfma_f32_16x16x32_bf16 v[0:3], v[156:159], v[218:221], v[0:3]
	s_setprio 0
	s_add_i32 s78, s78, 2
	s_add_u32 s6, s6, 0x100
	s_addc_u32 s7, s7, 0
	s_add_u32 s56, s56, 0x100
	s_addc_u32 s57, s57, 0
	s_cmp_gt_u32 s78, 13
	s_cbranch_scc0 .LBB0_323
	s_and_b64 vcc, exec, s[38:39]
	s_cbranch_vccz .LBB0_326
	s_barrier

.LBB0_697:
	s_and_b32 s29, s69, 0x1000
	s_add_i32 s70, s66, s29
	s_ashr_i32 s29, s28, 31
	ds_read_b128 v[0:3], v195 offset:3072
	ds_read_b128 v[4:7], v195 offset:2048
	ds_read_b128 v[8:11], v195 offset:1024
	ds_read_b128 v[12:15], v195
	ds_read_b128 v[16:19], v203 offset:3072
	ds_read_b128 v[20:23], v203 offset:2048
	ds_read_b128 v[24:27], v203 offset:1024
	ds_read_b128 v[28:31], v203
	s_lshl_b64 s[36:37], s[28:29], 20
	s_add_u32 s36, s50, s36
	s_addc_u32 s37, s51, s37
	s_and_b64 s[38:39], s[4:5], exec
	s_cselect_b32 s29, s37, s45
	s_cselect_b32 s71, s36, s44
	s_ashr_i32 s31, s30, 31
	s_lshl_b64 s[38:39], s[30:31], 20
	s_add_u32 s38, s54, s38
	s_addc_u32 s39, s55, s39
	s_and_b64 s[48:49], s[4:5], exec
	s_cselect_b32 s31, s39, s47
	s_cselect_b32 s72, s38, s46
	s_add_u32 s48, s44, 0x80080
	s_addc_u32 s49, s45, 0
	s_add_i32 s73, s56, 0xc000
	v_lshl_add_u64 v[64:65], s[48:49], 0, v[176:177]
	s_mov_b32 m0, s73
	s_add_i32 s74, s56, 0xe000
	ds_read_b128 v[32:35], v211
	ds_read_b128 v[36:39], v211 offset:1024
	ds_read_b128 v[40:43], v211 offset:2048
	ds_read_b128 v[44:47], v211 offset:3072
	ds_read_b128 v[48:51], v211 offset:4096
	ds_read_b128 v[52:55], v211 offset:5120
	ds_read_b128 v[56:59], v211 offset:6144
	ds_read_b128 v[60:63], v211 offset:7168
	global_load_lds_dwordx4 v[64:65], off
	v_lshl_add_u64 v[64:65], s[48:49], 0, v[178:179]
	s_mov_b32 m0, s74
	s_nop 0
	global_load_lds_dwordx4 v[64:65], off
	s_waitcnt vmcnt(8)
	s_waitcnt lgkmcnt(0)
	s_barrier
	s_setprio 1
	s_waitcnt lgkmcnt(0)
	v_mfma_f32_16x16x32_bf16 v[88:91], v[28:31], v[56:59], 0
	v_mfma_f32_16x16x32_bf16 v[64:67], v[28:31], v[32:35], 0
	v_mfma_f32_16x16x32_bf16 v[68:71], v[20:23], v[32:35], 0
	v_mfma_f32_16x16x32_bf16 v[72:75], v[28:31], v[40:43], 0
	v_mfma_f32_16x16x32_bf16 v[76:79], v[20:23], v[40:43], 0
	v_mfma_f32_16x16x32_bf16 v[80:83], v[28:31], v[48:51], 0
	v_mfma_f32_16x16x32_bf16 v[84:87], v[20:23], v[48:51], 0
	v_mfma_f32_16x16x32_bf16 v[96:99], v[24:27], v[60:63], v[88:91]
	v_mfma_f32_16x16x32_bf16 v[88:91], v[20:23], v[56:59], 0
	v_mfma_f32_16x16x32_bf16 v[64:67], v[24:27], v[36:39], v[64:67]
	v_mfma_f32_16x16x32_bf16 v[68:71], v[16:19], v[36:39], v[68:71]
	v_mfma_f32_16x16x32_bf16 v[72:75], v[24:27], v[44:47], v[72:75]
	v_mfma_f32_16x16x32_bf16 v[76:79], v[16:19], v[44:47], v[76:79]
	v_mfma_f32_16x16x32_bf16 v[80:83], v[24:27], v[52:55], v[80:83]
	v_mfma_f32_16x16x32_bf16 v[84:87], v[16:19], v[52:55], v[84:87]
	v_mfma_f32_16x16x32_bf16 v[100:103], v[16:19], v[60:63], v[88:91]
	s_setprio 0
	s_setprio 1
	v_mfma_f32_16x16x32_bf16 v[88:91], v[12:15], v[32:35], 0
	v_mfma_f32_16x16x32_bf16 v[32:35], v[4:7], v[32:35], 0
	v_mfma_f32_16x16x32_bf16 v[112:115], v[8:11], v[36:39], v[88:91]
	v_mfma_f32_16x16x32_bf16 v[32:35], v[0:3], v[36:39], v[32:35]
	v_mfma_f32_16x16x32_bf16 v[36:39], v[12:15], v[40:43], 0
	v_mfma_f32_16x16x32_bf16 v[40:43], v[4:7], v[40:43], 0
	v_mfma_f32_16x16x32_bf16 v[36:39], v[8:11], v[44:47], v[36:39]
	v_mfma_f32_16x16x32_bf16 v[40:43], v[0:3], v[44:47], v[40:43]
	v_mfma_f32_16x16x32_bf16 v[44:47], v[12:15], v[48:51], 0
	v_mfma_f32_16x16x32_bf16 v[48:51], v[4:7], v[48:51], 0
	v_mfma_f32_16x16x32_bf16 v[44:47], v[8:11], v[52:55], v[44:47]
	v_mfma_f32_16x16x32_bf16 v[48:51], v[0:3], v[52:55], v[48:51]
	s_setprio 2
	s_barrier
	v_mfma_f32_16x16x32_bf16 v[52:55], v[12:15], v[56:59], 0
	v_mfma_f32_16x16x32_bf16 v[56:59], v[4:7], v[56:59], 0
	v_mfma_f32_16x16x32_bf16 v[52:55], v[8:11], v[60:63], v[52:55]
	v_mfma_f32_16x16x32_bf16 v[56:59], v[0:3], v[60:63], v[56:59]
	s_setprio 0
	s_add_i32 s75, s68, s43
	v_lshl_add_u64 v[174:175], s[46:47], 0, v[176:177]
	s_add_i32 s76, s75, 0x2000
	v_lshl_add_u64 v[128:129], v[174:175], 0, s[24:25]
	s_mov_b32 m0, s75
	v_lshl_add_u64 v[200:201], s[46:47], 0, v[178:179]
	s_add_u32 s48, s46, 0x80100
	ds_read_b128 v[60:63], v211 offset:16384
	ds_read_b128 v[88:91], v211 offset:17408
	ds_read_b128 v[92:95], v211 offset:18432
	ds_read_b128 v[104:107], v211 offset:19456
	ds_read_b128 v[108:111], v211 offset:20480
	ds_read_b128 v[116:119], v211 offset:21504
	ds_read_b128 v[120:123], v211 offset:22528
	ds_read_b128 v[124:127], v211 offset:23552
	global_load_lds_dwordx4 v[128:129], off
	v_lshl_add_u64 v[128:129], v[200:201], 0, s[24:25]
	s_mov_b32 m0, s76
	s_addc_u32 s49, s47, 0
	s_add_i32 s77, s67, s43
	global_load_lds_dwordx4 v[128:129], off
	v_lshl_add_u64 v[128:129], s[48:49], 0, v[176:177]
	s_mov_b32 m0, s77
	s_add_i32 s78, s77, 0x2000
	global_load_lds_dwordx4 v[128:129], off
	v_lshl_add_u64 v[128:129], s[48:49], 0, v[178:179]
	s_mov_b32 m0, s78
	v_lshl_add_u64 v[208:209], s[44:45], 0, v[176:177]
	global_load_lds_dwordx4 v[128:129], off
	v_lshl_add_u64 v[128:129], v[208:209], 0, s[24:25]
	s_mov_b32 m0, s56
	v_lshl_add_u64 v[252:253], s[44:45], 0, v[178:179]
	global_load_lds_dwordx4 v[128:129], off
	v_lshl_add_u64 v[128:129], v[252:253], 0, s[24:25]
	s_mov_b32 m0, s57
	s_nop 0
	global_load_lds_dwordx4 v[128:129], off
	s_waitcnt vmcnt(8)
	s_waitcnt lgkmcnt(0)
	s_barrier
	s_setprio 1
	s_waitcnt lgkmcnt(0)
	v_mfma_f32_16x16x32_bf16 v[134:137], v[20:23], v[60:63], 0
	v_mfma_f32_16x16x32_bf16 v[142:145], v[20:23], v[92:95], 0
	v_mfma_f32_16x16x32_bf16 v[150:153], v[20:23], v[108:111], 0
	v_mfma_f32_16x16x32_bf16 v[20:23], v[20:23], v[120:123], 0
	v_mfma_f32_16x16x32_bf16 v[128:131], v[28:31], v[60:63], 0
	v_mfma_f32_16x16x32_bf16 v[134:137], v[16:19], v[88:91], v[134:137]
	v_mfma_f32_16x16x32_bf16 v[138:141], v[28:31], v[92:95], 0
	v_mfma_f32_16x16x32_bf16 v[142:145], v[16:19], v[104:107], v[142:145]
	v_mfma_f32_16x16x32_bf16 v[146:149], v[28:31], v[108:111], 0
	v_mfma_f32_16x16x32_bf16 v[150:153], v[16:19], v[116:119], v[150:153]
	v_mfma_f32_16x16x32_bf16 v[28:31], v[28:31], v[120:123], 0
	v_mfma_f32_16x16x32_bf16 v[16:19], v[16:19], v[124:127], v[20:23]
	v_mfma_f32_16x16x32_bf16 v[130:133], v[24:27], v[88:91], v[128:131]
	v_mfma_f32_16x16x32_bf16 v[138:141], v[24:27], v[104:107], v[138:141]
	v_mfma_f32_16x16x32_bf16 v[146:149], v[24:27], v[116:119], v[146:149]
	v_mfma_f32_16x16x32_bf16 v[154:157], v[24:27], v[124:127], v[28:31]
	s_setprio 0
	s_setprio 1
	v_mfma_f32_16x16x32_bf16 v[24:27], v[4:7], v[60:63], 0
	v_mfma_f32_16x16x32_bf16 v[158:161], v[0:3], v[88:91], v[24:27]
	v_mfma_f32_16x16x32_bf16 v[24:27], v[12:15], v[92:95], 0
	v_mfma_f32_16x16x32_bf16 v[162:165], v[8:11], v[104:107], v[24:27]
	v_mfma_f32_16x16x32_bf16 v[24:27], v[4:7], v[92:95], 0
	v_mfma_f32_16x16x32_bf16 v[166:169], v[0:3], v[104:107], v[24:27]
	v_mfma_f32_16x16x32_bf16 v[24:27], v[12:15], v[108:111], 0
	v_mfma_f32_16x16x32_bf16 v[20:23], v[12:15], v[60:63], 0
	v_mfma_f32_16x16x32_bf16 v[170:173], v[8:11], v[116:119], v[24:27]
	v_mfma_f32_16x16x32_bf16 v[24:27], v[4:7], v[108:111], 0
	v_mfma_f32_16x16x32_bf16 v[4:7], v[4:7], v[120:123], 0
	v_mfma_f32_16x16x32_bf16 v[20:23], v[8:11], v[88:91], v[20:23]
	s_setprio 2
	s_barrier
	v_mfma_f32_16x16x32_bf16 v[190:193], v[0:3], v[116:119], v[24:27]
	v_mfma_f32_16x16x32_bf16 v[12:15], v[12:15], v[120:123], 0
	v_mfma_f32_16x16x32_bf16 v[0:3], v[0:3], v[124:127], v[4:7]
	v_mfma_f32_16x16x32_bf16 v[196:199], v[8:11], v[124:127], v[12:15]
	s_setprio 0
	s_add_i32 s79, 0, 0x18000
	s_add_i32 s81, 0, 0x1c000
	v_add_u32_e32 v128, s79, v189
	v_add_u32_e32 v129, s81, v189
	ds_read_b128 v[4:7], v128
	ds_read_b128 v[8:11], v128 offset:1024
	ds_read_b128 v[204:207], v128 offset:2048
	ds_read_b128 v[212:215], v128 offset:3072
	ds_read_b128 v[216:219], v129
	ds_read_b128 v[220:223], v129 offset:1024
	ds_read_b128 v[224:227], v129 offset:2048
	ds_read_b128 v[228:231], v129 offset:3072
	s_add_u32 s48, s44, 0x80100
	s_addc_u32 s49, s45, 0
	s_mov_b32 m0, s58
	v_lshl_add_u64 v[88:89], s[48:49], 0, v[176:177]
	ds_read_b128 v[12:15], v211 offset:32768
	ds_read_b128 v[24:27], v211 offset:33792
	ds_read_b128 v[28:31], v211 offset:34816
	ds_read_b128 v[60:63], v211 offset:35840
	ds_read_b128 v[232:235], v211 offset:36864
	ds_read_b128 v[236:239], v211 offset:37888
	ds_read_b128 v[240:243], v211 offset:38912
	ds_read_b128 v[244:247], v211 offset:39936
	global_load_lds_dwordx4 v[88:89], off
	v_lshl_add_u64 v[88:89], s[48:49], 0, v[178:179]
	s_mov_b32 m0, s59
	s_nop 0
	global_load_lds_dwordx4 v[88:89], off
	s_waitcnt vmcnt(8)
	s_waitcnt lgkmcnt(0)
	s_barrier
	s_setprio 1
	s_waitcnt lgkmcnt(0)
	v_mfma_f32_16x16x32_bf16 v[64:67], v[4:7], v[12:15], v[64:67]
	v_mfma_f32_16x16x32_bf16 v[124:127], v[8:11], v[24:27], v[64:67]
	v_mfma_f32_16x16x32_bf16 v[64:67], v[204:207], v[12:15], v[68:71]
	v_mfma_f32_16x16x32_bf16 v[120:123], v[212:215], v[24:27], v[64:67]
	v_mfma_f32_16x16x32_bf16 v[64:67], v[4:7], v[28:31], v[72:75]
	v_mfma_f32_16x16x32_bf16 v[108:111], v[8:11], v[60:63], v[64:67]
	v_mfma_f32_16x16x32_bf16 v[64:67], v[204:207], v[28:31], v[76:79]
	v_mfma_f32_16x16x32_bf16 v[104:107], v[212:215], v[60:63], v[64:67]
	v_mfma_f32_16x16x32_bf16 v[64:67], v[4:7], v[232:235], v[80:83]
	v_mfma_f32_16x16x32_bf16 v[92:95], v[8:11], v[236:239], v[64:67]
	v_mfma_f32_16x16x32_bf16 v[64:67], v[204:207], v[232:235], v[84:87]
	v_mfma_f32_16x16x32_bf16 v[88:91], v[212:215], v[236:239], v[64:67]
	v_mfma_f32_16x16x32_bf16 v[64:67], v[4:7], v[240:243], v[96:99]
	v_mfma_f32_16x16x32_bf16 v[76:79], v[8:11], v[244:247], v[64:67]
	v_mfma_f32_16x16x32_bf16 v[64:67], v[204:207], v[240:243], v[100:103]
	v_mfma_f32_16x16x32_bf16 v[72:75], v[212:215], v[244:247], v[64:67]
	s_setprio 0
	s_setprio 1
	v_mfma_f32_16x16x32_bf16 v[64:67], v[216:219], v[12:15], v[112:115]
	v_mfma_f32_16x16x32_bf16 v[12:15], v[224:227], v[12:15], v[32:35]
	v_mfma_f32_16x16x32_bf16 v[112:115], v[228:231], v[24:27], v[12:15]
	v_mfma_f32_16x16x32_bf16 v[12:15], v[216:219], v[28:31], v[36:39]
	v_mfma_f32_16x16x32_bf16 v[100:103], v[220:223], v[60:63], v[12:15]
	v_mfma_f32_16x16x32_bf16 v[12:15], v[224:227], v[28:31], v[40:43]
	v_mfma_f32_16x16x32_bf16 v[96:99], v[228:231], v[60:63], v[12:15]
	v_mfma_f32_16x16x32_bf16 v[12:15], v[216:219], v[232:235], v[44:47]
	v_mfma_f32_16x16x32_bf16 v[84:87], v[220:223], v[236:239], v[12:15]
	v_mfma_f32_16x16x32_bf16 v[12:15], v[224:227], v[232:235], v[48:51]
	v_mfma_f32_16x16x32_bf16 v[80:83], v[228:231], v[236:239], v[12:15]
	v_mfma_f32_16x16x32_bf16 v[12:15], v[216:219], v[240:243], v[52:55]
	s_setprio 2
	s_barrier
	v_mfma_f32_16x16x32_bf16 v[68:71], v[220:223], v[244:247], v[12:15]
	v_mfma_f32_16x16x32_bf16 v[12:15], v[224:227], v[240:243], v[56:59]
	v_mfma_f32_16x16x32_bf16 v[116:119], v[220:223], v[24:27], v[64:67]
	v_mfma_f32_16x16x32_bf16 v[64:67], v[228:231], v[244:247], v[12:15]
	s_setprio 0
	s_add_i32 s79, s79, s43
	s_add_i32 s80, s79, 0x2000
	s_nop 1
	v_lshl_add_u64 v[12:13], v[174:175], 0, s[26:27]
	s_mov_b32 m0, s79
	s_add_u32 s48, s46, 0x80180
	ds_read_b128 v[32:35], v211 offset:49152
	ds_read_b128 v[36:39], v211 offset:50176
	ds_read_b128 v[232:235], v211 offset:51200
	ds_read_b128 v[236:239], v211 offset:52224
	ds_read_b128 v[240:243], v211 offset:53248
	ds_read_b128 v[244:247], v211 offset:54272
	ds_read_b128 v[248:251], v211 offset:55296
	ds_read_b128 v[184:187], v211 offset:56320
	global_load_lds_dwordx4 v[12:13], off
	v_lshl_add_u64 v[12:13], v[200:201], 0, s[26:27]
	s_mov_b32 m0, s80
	s_addc_u32 s49, s47, 0
	s_add_i32 s81, s81, s43
	global_load_lds_dwordx4 v[12:13], off
	v_lshl_add_u64 v[12:13], s[48:49], 0, v[176:177]
	s_mov_b32 m0, s81
	s_add_i32 s82, s81, 0x2000
	global_load_lds_dwordx4 v[12:13], off
	v_lshl_add_u64 v[12:13], s[48:49], 0, v[178:179]
	s_mov_b32 m0, s82
	s_nop 0
	global_load_lds_dwordx4 v[12:13], off
	v_lshl_add_u64 v[12:13], v[208:209], 0, s[26:27]
	s_mov_b32 m0, s61
	s_nop 0
	global_load_lds_dwordx4 v[12:13], off
	v_lshl_add_u64 v[12:13], v[252:253], 0, s[26:27]
	s_mov_b32 m0, s62
	s_nop 0
	global_load_lds_dwordx4 v[12:13], off
	s_waitcnt vmcnt(8)
	s_waitcnt lgkmcnt(0)
	s_barrier
	s_setprio 1
	s_waitcnt lgkmcnt(0)
	v_mfma_f32_16x16x32_bf16 v[12:15], v[4:7], v[32:35], v[130:133]
	v_mfma_f32_16x16x32_bf16 v[60:63], v[8:11], v[36:39], v[12:15]
	v_mfma_f32_16x16x32_bf16 v[12:15], v[204:207], v[32:35], v[134:137]
	v_mfma_f32_16x16x32_bf16 v[56:59], v[212:215], v[36:39], v[12:15]
	v_mfma_f32_16x16x32_bf16 v[12:15], v[4:7], v[232:235], v[138:141]
	v_mfma_f32_16x16x32_bf16 v[44:47], v[8:11], v[236:239], v[12:15]
	v_mfma_f32_16x16x32_bf16 v[12:15], v[204:207], v[232:235], v[142:145]
	v_mfma_f32_16x16x32_bf16 v[40:43], v[212:215], v[236:239], v[12:15]
	v_mfma_f32_16x16x32_bf16 v[12:15], v[4:7], v[240:243], v[146:149]
	v_mfma_f32_16x16x32_bf16 v[28:31], v[8:11], v[244:247], v[12:15]
	v_mfma_f32_16x16x32_bf16 v[12:15], v[204:207], v[240:243], v[150:153]
	v_mfma_f32_16x16x32_bf16 v[4:7], v[4:7], v[248:251], v[154:157]
	v_mfma_f32_16x16x32_bf16 v[24:27], v[212:215], v[244:247], v[12:15]
	v_mfma_f32_16x16x32_bf16 v[12:15], v[8:11], v[184:187], v[4:7]
	v_mfma_f32_16x16x32_bf16 v[4:7], v[204:207], v[248:251], v[16:19]
	v_mfma_f32_16x16x32_bf16 v[8:11], v[212:215], v[184:187], v[4:7]
	s_setprio 0
	s_setprio 1
	v_mfma_f32_16x16x32_bf16 v[4:7], v[216:219], v[32:35], v[20:23]
	v_mfma_f32_16x16x32_bf16 v[52:55], v[220:223], v[36:39], v[4:7]
	v_mfma_f32_16x16x32_bf16 v[4:7], v[224:227], v[32:35], v[158:161]
	v_mfma_f32_16x16x32_bf16 v[48:51], v[228:231], v[36:39], v[4:7]
	v_mfma_f32_16x16x32_bf16 v[4:7], v[216:219], v[232:235], v[162:165]
	v_mfma_f32_16x16x32_bf16 v[36:39], v[220:223], v[236:239], v[4:7]
	v_mfma_f32_16x16x32_bf16 v[4:7], v[224:227], v[232:235], v[166:169]
	v_mfma_f32_16x16x32_bf16 v[32:35], v[228:231], v[236:239], v[4:7]
	v_mfma_f32_16x16x32_bf16 v[4:7], v[216:219], v[240:243], v[170:173]
	v_mfma_f32_16x16x32_bf16 v[20:23], v[220:223], v[244:247], v[4:7]
	v_mfma_f32_16x16x32_bf16 v[4:7], v[224:227], v[240:243], v[190:193]
	v_mfma_f32_16x16x32_bf16 v[16:19], v[228:231], v[244:247], v[4:7]
	s_setprio 2
	s_barrier
	v_mfma_f32_16x16x32_bf16 v[4:7], v[216:219], v[248:251], v[196:199]
	v_mfma_f32_16x16x32_bf16 v[0:3], v[224:227], v[248:251], v[0:3]
	v_mfma_f32_16x16x32_bf16 v[4:7], v[220:223], v[184:187], v[4:7]
	v_mfma_f32_16x16x32_bf16 v[0:3], v[228:231], v[184:187], v[0:3]
	s_setprio 0
	s_add_u32 s44, s44, 0x80180
	s_addc_u32 s45, s45, 0
	s_add_u32 s83, s46, 0x200
	s_addc_u32 s84, s47, 0
	s_mov_b32 s46, 0
	s_add_i32 s85, s46, 2
	s_and_b32 s47, s85, 6
	s_cmp_lg_u32 s47, 0
	s_cbranch_scc1 .LBB0_700
	s_branch .LBB0_699

.LBB0_700:
	ds_read_b128 v[130:133], v203
	ds_read_b128 v[134:137], v203 offset:1024
	ds_read_b128 v[138:141], v203 offset:2048
	ds_read_b128 v[142:145], v203 offset:3072
	ds_read_b128 v[146:149], v195
	ds_read_b128 v[150:153], v195 offset:1024
	ds_read_b128 v[154:157], v195 offset:2048
	ds_read_b128 v[158:161], v195 offset:3072
	s_add_u32 s47, s44, 0xfff80080
	s_addc_u32 s48, s45, -1
	s_cmp_eq_u32 s46, 28
	s_cselect_b32 s49, s29, s48
	s_cselect_b32 s48, s71, s47
	s_cselect_b32 s47, s31, s84
	s_cselect_b32 s46, s72, s83
	s_mov_b32 m0, s73
	v_lshl_add_u64 v[174:175], s[44:45], 0, v[180:181]
	ds_read_b128 v[162:165], v211
	ds_read_b128 v[166:169], v211 offset:1024
	ds_read_b128 v[170:173], v211 offset:2048
	ds_read_b128 v[184:187], v211 offset:3072
	ds_read_b128 v[190:193], v211 offset:4096
	ds_read_b128 v[196:199], v211 offset:5120
	ds_read_b128 v[204:207], v211 offset:6144
	ds_read_b128 v[212:215], v211 offset:7168
	global_load_lds_dwordx4 v[174:175], off
	v_lshl_add_u64 v[174:175], s[44:45], 0, v[182:183]
	s_mov_b32 m0, s74
	s_nop 0
	global_load_lds_dwordx4 v[174:175], off
	s_waitcnt vmcnt(8)
	s_waitcnt lgkmcnt(0)
	s_barrier
	s_setprio 1
	s_waitcnt lgkmcnt(0)
	v_mfma_f32_16x16x32_bf16 v[124:127], v[130:133], v[162:165], v[124:127]
	v_mfma_f32_16x16x32_bf16 v[120:123], v[138:141], v[162:165], v[120:123]
	v_mfma_f32_16x16x32_bf16 v[108:111], v[130:133], v[170:173], v[108:111]
	v_mfma_f32_16x16x32_bf16 v[104:107], v[138:141], v[170:173], v[104:107]
	v_mfma_f32_16x16x32_bf16 v[92:95], v[130:133], v[190:193], v[92:95]
	v_mfma_f32_16x16x32_bf16 v[88:91], v[138:141], v[190:193], v[88:91]
	v_mfma_f32_16x16x32_bf16 v[76:79], v[130:133], v[204:207], v[76:79]
	v_mfma_f32_16x16x32_bf16 v[72:75], v[138:141], v[204:207], v[72:75]
	v_mfma_f32_16x16x32_bf16 v[124:127], v[134:137], v[166:169], v[124:127]
	v_mfma_f32_16x16x32_bf16 v[120:123], v[142:145], v[166:169], v[120:123]
	v_mfma_f32_16x16x32_bf16 v[108:111], v[134:137], v[184:187], v[108:111]
	v_mfma_f32_16x16x32_bf16 v[104:107], v[142:145], v[184:187], v[104:107]
	v_mfma_f32_16x16x32_bf16 v[92:95], v[134:137], v[196:199], v[92:95]
	v_mfma_f32_16x16x32_bf16 v[88:91], v[142:145], v[196:199], v[88:91]
	v_mfma_f32_16x16x32_bf16 v[76:79], v[134:137], v[212:215], v[76:79]
	v_mfma_f32_16x16x32_bf16 v[72:75], v[142:145], v[212:215], v[72:75]
	s_setprio 0
	s_setprio 1
	v_mfma_f32_16x16x32_bf16 v[116:119], v[146:149], v[162:165], v[116:119]
	v_mfma_f32_16x16x32_bf16 v[112:115], v[154:157], v[162:165], v[112:115]
	v_mfma_f32_16x16x32_bf16 v[100:103], v[146:149], v[170:173], v[100:103]
	v_mfma_f32_16x16x32_bf16 v[96:99], v[154:157], v[170:173], v[96:99]
	v_mfma_f32_16x16x32_bf16 v[84:87], v[146:149], v[190:193], v[84:87]
	v_mfma_f32_16x16x32_bf16 v[80:83], v[154:157], v[190:193], v[80:83]
	v_mfma_f32_16x16x32_bf16 v[68:71], v[146:149], v[204:207], v[68:71]
	v_mfma_f32_16x16x32_bf16 v[64:67], v[154:157], v[204:207], v[64:67]
	v_mfma_f32_16x16x32_bf16 v[116:119], v[150:153], v[166:169], v[116:119]
	v_mfma_f32_16x16x32_bf16 v[112:115], v[158:161], v[166:169], v[112:115]
	v_mfma_f32_16x16x32_bf16 v[100:103], v[150:153], v[184:187], v[100:103]
	v_mfma_f32_16x16x32_bf16 v[96:99], v[158:161], v[184:187], v[96:99]
	s_setprio 2
	s_barrier
	v_mfma_f32_16x16x32_bf16 v[84:87], v[150:153], v[196:199], v[84:87]
	v_mfma_f32_16x16x32_bf16 v[80:83], v[158:161], v[196:199], v[80:83]
	v_mfma_f32_16x16x32_bf16 v[68:71], v[150:153], v[212:215], v[68:71]
	v_mfma_f32_16x16x32_bf16 v[64:67], v[158:161], v[212:215], v[64:67]
	s_setprio 0
	s_mov_b32 m0, s75
	v_lshl_add_u64 v[174:175], s[46:47], 0, v[176:177]
	s_add_u32 s86, s46, 0x80000
	ds_read_b128 v[162:165], v211 offset:16384
	ds_read_b128 v[166:169], v211 offset:17408
	ds_read_b128 v[170:173], v211 offset:18432
	ds_read_b128 v[184:187], v211 offset:19456
	ds_read_b128 v[190:193], v211 offset:20480
	ds_read_b128 v[196:199], v211 offset:21504
	ds_read_b128 v[204:207], v211 offset:22528
	ds_read_b128 v[212:215], v211 offset:23552
	global_load_lds_dwordx4 v[174:175], off
	v_lshl_add_u64 v[200:201], s[46:47], 0, v[178:179]
	s_mov_b32 m0, s76
	s_addc_u32 s87, s47, 0
	global_load_lds_dwordx4 v[200:201], off
	v_lshl_add_u64 v[208:209], s[86:87], 0, v[176:177]
	s_mov_b32 m0, s77
	v_lshl_add_u64 v[216:217], s[48:49], 0, v[178:179]
	global_load_lds_dwordx4 v[208:209], off
	v_lshl_add_u64 v[208:209], s[86:87], 0, v[178:179]
	s_mov_b32 m0, s78
	s_nop 0
	global_load_lds_dwordx4 v[208:209], off
	v_lshl_add_u64 v[208:209], s[48:49], 0, v[176:177]
	s_mov_b32 m0, s56
	s_nop 0
	global_load_lds_dwordx4 v[208:209], off
	s_mov_b32 m0, s57
	s_nop 0
	global_load_lds_dwordx4 v[216:217], off
	s_waitcnt vmcnt(8)
	s_waitcnt lgkmcnt(0)
	s_barrier
	s_setprio 1
	s_waitcnt lgkmcnt(0)
	v_mfma_f32_16x16x32_bf16 v[60:63], v[130:133], v[162:165], v[60:63]
	v_mfma_f32_16x16x32_bf16 v[56:59], v[138:141], v[162:165], v[56:59]
	v_mfma_f32_16x16x32_bf16 v[44:47], v[130:133], v[170:173], v[44:47]
	v_mfma_f32_16x16x32_bf16 v[40:43], v[138:141], v[170:173], v[40:43]
	v_mfma_f32_16x16x32_bf16 v[28:31], v[130:133], v[190:193], v[28:31]
	v_mfma_f32_16x16x32_bf16 v[24:27], v[138:141], v[190:193], v[24:27]
	v_mfma_f32_16x16x32_bf16 v[12:15], v[130:133], v[204:207], v[12:15]
	v_mfma_f32_16x16x32_bf16 v[8:11], v[138:141], v[204:207], v[8:11]
	v_mfma_f32_16x16x32_bf16 v[60:63], v[134:137], v[166:169], v[60:63]
	v_mfma_f32_16x16x32_bf16 v[56:59], v[142:145], v[166:169], v[56:59]
	v_mfma_f32_16x16x32_bf16 v[44:47], v[134:137], v[184:187], v[44:47]
	v_mfma_f32_16x16x32_bf16 v[40:43], v[142:145], v[184:187], v[40:43]
	v_mfma_f32_16x16x32_bf16 v[28:31], v[134:137], v[196:199], v[28:31]
	v_mfma_f32_16x16x32_bf16 v[24:27], v[142:145], v[196:199], v[24:27]
	v_mfma_f32_16x16x32_bf16 v[12:15], v[134:137], v[212:215], v[12:15]
	v_mfma_f32_16x16x32_bf16 v[8:11], v[142:145], v[212:215], v[8:11]
	s_setprio 0
	s_setprio 1
	v_mfma_f32_16x16x32_bf16 v[52:55], v[146:149], v[162:165], v[52:55]
	v_mfma_f32_16x16x32_bf16 v[48:51], v[154:157], v[162:165], v[48:51]
	v_mfma_f32_16x16x32_bf16 v[36:39], v[146:149], v[170:173], v[36:39]
	v_mfma_f32_16x16x32_bf16 v[32:35], v[154:157], v[170:173], v[32:35]
	v_mfma_f32_16x16x32_bf16 v[20:23], v[146:149], v[190:193], v[20:23]
	v_mfma_f32_16x16x32_bf16 v[16:19], v[154:157], v[190:193], v[16:19]
	v_mfma_f32_16x16x32_bf16 v[4:7], v[146:149], v[204:207], v[4:7]
	v_mfma_f32_16x16x32_bf16 v[0:3], v[154:157], v[204:207], v[0:3]
	v_mfma_f32_16x16x32_bf16 v[52:55], v[150:153], v[166:169], v[52:55]
	v_mfma_f32_16x16x32_bf16 v[48:51], v[158:161], v[166:169], v[48:51]
	v_mfma_f32_16x16x32_bf16 v[36:39], v[150:153], v[184:187], v[36:39]
	v_mfma_f32_16x16x32_bf16 v[32:35], v[158:161], v[184:187], v[32:35]
	s_setprio 2
	s_barrier
	v_mfma_f32_16x16x32_bf16 v[20:23], v[150:153], v[196:199], v[20:23]
	v_mfma_f32_16x16x32_bf16 v[16:19], v[158:161], v[196:199], v[16:19]
	v_mfma_f32_16x16x32_bf16 v[4:7], v[150:153], v[212:215], v[4:7]
	v_mfma_f32_16x16x32_bf16 v[0:3], v[158:161], v[212:215], v[0:3]
	s_setprio 0
	ds_read_b128 v[130:133], v128
	ds_read_b128 v[134:137], v128 offset:1024
	ds_read_b128 v[138:141], v128 offset:2048
	ds_read_b128 v[142:145], v128 offset:3072
	ds_read_b128 v[146:149], v129
	ds_read_b128 v[150:153], v129 offset:1024
	ds_read_b128 v[154:157], v129 offset:2048
	ds_read_b128 v[158:161], v129 offset:3072
	s_add_u32 s48, s48, 0x80000
	s_addc_u32 s49, s49, 0
	s_mov_b32 m0, s58
	v_lshl_add_u64 v[218:219], s[48:49], 0, v[176:177]
	ds_read_b128 v[162:165], v211 offset:32768
	ds_read_b128 v[166:169], v211 offset:33792
	ds_read_b128 v[170:173], v211 offset:34816
	ds_read_b128 v[184:187], v211 offset:35840
	ds_read_b128 v[190:193], v211 offset:36864
	ds_read_b128 v[196:199], v211 offset:37888
	ds_read_b128 v[204:207], v211 offset:38912
	ds_read_b128 v[212:215], v211 offset:39936
	global_load_lds_dwordx4 v[218:219], off
	v_lshl_add_u64 v[218:219], s[48:49], 0, v[178:179]
	s_mov_b32 m0, s59
	s_nop 0
	global_load_lds_dwordx4 v[218:219], off
	s_waitcnt vmcnt(8)
	s_waitcnt lgkmcnt(0)
	s_barrier
	s_setprio 1
	s_waitcnt lgkmcnt(0)
	v_mfma_f32_16x16x32_bf16 v[124:127], v[130:133], v[162:165], v[124:127]
	v_mfma_f32_16x16x32_bf16 v[120:123], v[138:141], v[162:165], v[120:123]
	v_mfma_f32_16x16x32_bf16 v[108:111], v[130:133], v[170:173], v[108:111]
	v_mfma_f32_16x16x32_bf16 v[104:107], v[138:141], v[170:173], v[104:107]
	v_mfma_f32_16x16x32_bf16 v[92:95], v[130:133], v[190:193], v[92:95]
	v_mfma_f32_16x16x32_bf16 v[88:91], v[138:141], v[190:193], v[88:91]
	v_mfma_f32_16x16x32_bf16 v[76:79], v[130:133], v[204:207], v[76:79]
	v_mfma_f32_16x16x32_bf16 v[72:75], v[138:141], v[204:207], v[72:75]
	v_mfma_f32_16x16x32_bf16 v[124:127], v[134:137], v[166:169], v[124:127]
	v_mfma_f32_16x16x32_bf16 v[120:123], v[142:145], v[166:169], v[120:123]
	v_mfma_f32_16x16x32_bf16 v[108:111], v[134:137], v[184:187], v[108:111]
	v_mfma_f32_16x16x32_bf16 v[104:107], v[142:145], v[184:187], v[104:107]
	v_mfma_f32_16x16x32_bf16 v[92:95], v[134:137], v[196:199], v[92:95]
	v_mfma_f32_16x16x32_bf16 v[88:91], v[142:145], v[196:199], v[88:91]
	v_mfma_f32_16x16x32_bf16 v[76:79], v[134:137], v[212:215], v[76:79]
	v_mfma_f32_16x16x32_bf16 v[72:75], v[142:145], v[212:215], v[72:75]
	s_setprio 0
	s_setprio 1
	v_mfma_f32_16x16x32_bf16 v[116:119], v[146:149], v[162:165], v[116:119]
	v_mfma_f32_16x16x32_bf16 v[112:115], v[154:157], v[162:165], v[112:115]
	v_mfma_f32_16x16x32_bf16 v[100:103], v[146:149], v[170:173], v[100:103]
	v_mfma_f32_16x16x32_bf16 v[96:99], v[154:157], v[170:173], v[96:99]
	v_mfma_f32_16x16x32_bf16 v[84:87], v[146:149], v[190:193], v[84:87]
	v_mfma_f32_16x16x32_bf16 v[80:83], v[154:157], v[190:193], v[80:83]
	v_mfma_f32_16x16x32_bf16 v[68:71], v[146:149], v[204:207], v[68:71]
	v_mfma_f32_16x16x32_bf16 v[64:67], v[154:157], v[204:207], v[64:67]
	v_mfma_f32_16x16x32_bf16 v[116:119], v[150:153], v[166:169], v[116:119]
	v_mfma_f32_16x16x32_bf16 v[112:115], v[158:161], v[166:169], v[112:115]
	v_mfma_f32_16x16x32_bf16 v[100:103], v[150:153], v[184:187], v[100:103]
	v_mfma_f32_16x16x32_bf16 v[96:99], v[158:161], v[184:187], v[96:99]
	s_setprio 2
	s_barrier
	v_mfma_f32_16x16x32_bf16 v[84:87], v[150:153], v[196:199], v[84:87]
	v_mfma_f32_16x16x32_bf16 v[80:83], v[158:161], v[196:199], v[80:83]
	v_mfma_f32_16x16x32_bf16 v[68:71], v[150:153], v[212:215], v[68:71]
	v_mfma_f32_16x16x32_bf16 v[64:67], v[158:161], v[212:215], v[64:67]
	s_setprio 0
	s_mov_b32 m0, s79
	v_lshl_add_u64 v[174:175], v[174:175], 0, s[20:21]
	s_add_u32 s46, s46, 0x80080
	ds_read_b128 v[162:165], v211 offset:49152
	ds_read_b128 v[166:169], v211 offset:50176
	ds_read_b128 v[170:173], v211 offset:51200
	ds_read_b128 v[184:187], v211 offset:52224
	ds_read_b128 v[190:193], v211 offset:53248
	ds_read_b128 v[196:199], v211 offset:54272
	ds_read_b128 v[204:207], v211 offset:55296
	ds_read_b128 v[212:215], v211 offset:56320
	global_load_lds_dwordx4 v[174:175], off
	v_lshl_add_u64 v[174:175], v[200:201], 0, s[20:21]
	s_mov_b32 m0, s80
	s_addc_u32 s47, s47, 0
	global_load_lds_dwordx4 v[174:175], off
	v_lshl_add_u64 v[174:175], s[46:47], 0, v[176:177]
	s_mov_b32 m0, s81
	s_nop 0
	global_load_lds_dwordx4 v[174:175], off
	v_lshl_add_u64 v[174:175], s[46:47], 0, v[178:179]
	s_mov_b32 m0, s82
	s_nop 0
	global_load_lds_dwordx4 v[174:175], off
	v_lshl_add_u64 v[174:175], v[208:209], 0, s[20:21]
	s_mov_b32 m0, s61
	s_nop 0
	global_load_lds_dwordx4 v[174:175], off
	v_lshl_add_u64 v[174:175], v[216:217], 0, s[20:21]
	s_mov_b32 m0, s62
	s_nop 0
	global_load_lds_dwordx4 v[174:175], off
	s_waitcnt vmcnt(8)
	s_waitcnt lgkmcnt(0)
	s_barrier
	s_setprio 1
	s_waitcnt lgkmcnt(0)
	v_mfma_f32_16x16x32_bf16 v[60:63], v[130:133], v[162:165], v[60:63]
	v_mfma_f32_16x16x32_bf16 v[56:59], v[138:141], v[162:165], v[56:59]
	v_mfma_f32_16x16x32_bf16 v[44:47], v[130:133], v[170:173], v[44:47]
	v_mfma_f32_16x16x32_bf16 v[40:43], v[138:141], v[170:173], v[40:43]
	v_mfma_f32_16x16x32_bf16 v[28:31], v[130:133], v[190:193], v[28:31]
	v_mfma_f32_16x16x32_bf16 v[24:27], v[138:141], v[190:193], v[24:27]
	v_mfma_f32_16x16x32_bf16 v[12:15], v[130:133], v[204:207], v[12:15]
	v_mfma_f32_16x16x32_bf16 v[8:11], v[138:141], v[204:207], v[8:11]
	v_mfma_f32_16x16x32_bf16 v[60:63], v[134:137], v[166:169], v[60:63]
	v_mfma_f32_16x16x32_bf16 v[56:59], v[142:145], v[166:169], v[56:59]
	v_mfma_f32_16x16x32_bf16 v[44:47], v[134:137], v[184:187], v[44:47]
	v_mfma_f32_16x16x32_bf16 v[40:43], v[142:145], v[184:187], v[40:43]
	v_mfma_f32_16x16x32_bf16 v[28:31], v[134:137], v[196:199], v[28:31]
	v_mfma_f32_16x16x32_bf16 v[24:27], v[142:145], v[196:199], v[24:27]
	v_mfma_f32_16x16x32_bf16 v[12:15], v[134:137], v[212:215], v[12:15]
	v_mfma_f32_16x16x32_bf16 v[8:11], v[142:145], v[212:215], v[8:11]
	s_setprio 0
	s_setprio 1
	v_mfma_f32_16x16x32_bf16 v[52:55], v[146:149], v[162:165], v[52:55]
	v_mfma_f32_16x16x32_bf16 v[48:51], v[154:157], v[162:165], v[48:51]
	v_mfma_f32_16x16x32_bf16 v[36:39], v[146:149], v[170:173], v[36:39]
	v_mfma_f32_16x16x32_bf16 v[32:35], v[154:157], v[170:173], v[32:35]
	v_mfma_f32_16x16x32_bf16 v[20:23], v[146:149], v[190:193], v[20:23]
	v_mfma_f32_16x16x32_bf16 v[16:19], v[154:157], v[190:193], v[16:19]
	v_mfma_f32_16x16x32_bf16 v[4:7], v[146:149], v[204:207], v[4:7]
	v_mfma_f32_16x16x32_bf16 v[0:3], v[154:157], v[204:207], v[0:3]
	v_mfma_f32_16x16x32_bf16 v[52:55], v[150:153], v[166:169], v[52:55]
	v_mfma_f32_16x16x32_bf16 v[48:51], v[158:161], v[166:169], v[48:51]
	v_mfma_f32_16x16x32_bf16 v[36:39], v[150:153], v[184:187], v[36:39]
	v_mfma_f32_16x16x32_bf16 v[32:35], v[158:161], v[184:187], v[32:35]
	s_setprio 2
	s_barrier
	v_mfma_f32_16x16x32_bf16 v[20:23], v[150:153], v[196:199], v[20:23]
	v_mfma_f32_16x16x32_bf16 v[16:19], v[158:161], v[196:199], v[16:19]
	v_mfma_f32_16x16x32_bf16 v[4:7], v[150:153], v[212:215], v[4:7]
	v_mfma_f32_16x16x32_bf16 v[0:3], v[158:161], v[212:215], v[0:3]
	s_setprio 0
	s_add_i32 s70, s70, 1
	s_add_u32 s44, s44, 0x100
	s_addc_u32 s45, s45, 0
	s_add_u32 s83, s83, 0x100
	s_addc_u32 s84, s84, 0
	s_cmp_gt_u32 s85, 29
	s_cbranch_scc0 .LBB0_698
	s_lshl_b32 s29, s41, 12
	s_and_b32 s29, s29, 0x1000
	s_add_i32 s29, s29, 0
	v_mbcnt_lo_u32_b32 v128, -1, 0
	v_mbcnt_hi_u32_b32 v128, -1, v128
	s_add_i32 s29, s29, s63
	v_lshlrev_b32_e32 v128, 4, v128
	s_add_i32 s29, s29, 0x20400
	v_and_b32_e32 v128, 0xf0, v128
	v_add_u32_e32 v128, s29, v128
	ds_read2_b32 v[214:215], v128 offset0:3 offset1:67
	ds_read2_b32 v[206:207], v128 offset0:131 offset1:195
	v_add_u32_e32 v128, 12, v128
	ds_read2st64_b32 v[196:197], v128 offset0:8 offset1:9
	ds_read2st64_b32 v[190:191], v128 offset0:10 offset1:11
	s_and_b64 vcc, exec, s[22:23]
	s_waitcnt lgkmcnt(0)
	v_mov_b32_e32 v210, v215
	v_mov_b32_e32 v202, v207
	v_mov_b32_e32 v194, v197
	v_mov_b32_e32 v188, v191
	s_cbranch_vccz .LBB0_703
	s_barrier

.LBB0_784:
	ds_read_b128 v[144:147], v163
	ds_read_b128 v[148:151], v163 offset:1024
	ds_read_b128 v[152:155], v163 offset:2048
	ds_read_b128 v[156:159], v163 offset:3072
	ds_read_b128 v[168:171], v164
	ds_read_b128 v[172:175], v164 offset:1024
	ds_read_b128 v[176:179], v164 offset:2048
	ds_read_b128 v[180:183], v164 offset:3072
	s_add_u32 s38, s36, 0xfffc0080
	s_addc_u32 s39, s37, -1
	s_cmp_eq_u32 s65, 12
	s_cselect_b32 s41, s23, s39
	s_cselect_b32 s40, s31, s38
	s_cselect_b32 s39, s25, s64
	s_cselect_b32 s38, s62, s63
	v_lshl_add_u64 v[160:161], s[36:37], 0, v[136:137]
	s_add_i32 m0, s50, 0xc000
	ds_read_b128 v[184:187], v165
	ds_read_b128 v[188:191], v165 offset:1024
	ds_read_b128 v[192:195], v165 offset:2048
	ds_read_b128 v[196:199], v165 offset:3072
	ds_read_b128 v[200:203], v165 offset:4096
	ds_read_b128 v[204:207], v165 offset:5120
	ds_read_b128 v[208:211], v165 offset:6144
	ds_read_b128 v[212:215], v165 offset:7168
	global_load_lds_dwordx4 v[160:161], off
	v_lshl_add_u64 v[160:161], s[36:37], 0, v[138:139]
	s_add_i32 m0, s50, 0xe000
	s_nop 0
	global_load_lds_dwordx4 v[160:161], off
	s_waitcnt vmcnt(8)
	s_waitcnt lgkmcnt(0)
	s_barrier
	s_setprio 1
	s_waitcnt lgkmcnt(0)
	v_mfma_f32_16x16x32_bf16 v[124:127], v[144:147], v[184:187], v[124:127]
	v_mfma_f32_16x16x32_bf16 v[120:123], v[152:155], v[184:187], v[120:123]
	v_mfma_f32_16x16x32_bf16 v[108:111], v[144:147], v[192:195], v[108:111]
	v_mfma_f32_16x16x32_bf16 v[104:107], v[152:155], v[192:195], v[104:107]
	v_mfma_f32_16x16x32_bf16 v[92:95], v[144:147], v[200:203], v[92:95]
	v_mfma_f32_16x16x32_bf16 v[88:91], v[152:155], v[200:203], v[88:91]
	v_mfma_f32_16x16x32_bf16 v[76:79], v[144:147], v[208:211], v[76:79]
	v_mfma_f32_16x16x32_bf16 v[72:75], v[152:155], v[208:211], v[72:75]
	v_mfma_f32_16x16x32_bf16 v[124:127], v[148:151], v[188:191], v[124:127]
	v_mfma_f32_16x16x32_bf16 v[120:123], v[156:159], v[188:191], v[120:123]
	v_mfma_f32_16x16x32_bf16 v[108:111], v[148:151], v[196:199], v[108:111]
	v_mfma_f32_16x16x32_bf16 v[104:107], v[156:159], v[196:199], v[104:107]
	v_mfma_f32_16x16x32_bf16 v[92:95], v[148:151], v[204:207], v[92:95]
	v_mfma_f32_16x16x32_bf16 v[88:91], v[156:159], v[204:207], v[88:91]
	v_mfma_f32_16x16x32_bf16 v[76:79], v[148:151], v[212:215], v[76:79]
	v_mfma_f32_16x16x32_bf16 v[72:75], v[156:159], v[212:215], v[72:75]
	s_setprio 0
	s_setprio 1
	v_mfma_f32_16x16x32_bf16 v[116:119], v[168:171], v[184:187], v[116:119]
	v_mfma_f32_16x16x32_bf16 v[112:115], v[176:179], v[184:187], v[112:115]
	v_mfma_f32_16x16x32_bf16 v[100:103], v[168:171], v[192:195], v[100:103]
	v_mfma_f32_16x16x32_bf16 v[96:99], v[176:179], v[192:195], v[96:99]
	v_mfma_f32_16x16x32_bf16 v[84:87], v[168:171], v[200:203], v[84:87]
	v_mfma_f32_16x16x32_bf16 v[80:83], v[176:179], v[200:203], v[80:83]
	v_mfma_f32_16x16x32_bf16 v[68:71], v[168:171], v[208:211], v[68:71]
	v_mfma_f32_16x16x32_bf16 v[64:67], v[176:179], v[208:211], v[64:67]
	v_mfma_f32_16x16x32_bf16 v[116:119], v[172:175], v[188:191], v[116:119]
	v_mfma_f32_16x16x32_bf16 v[112:115], v[180:183], v[188:191], v[112:115]
	v_mfma_f32_16x16x32_bf16 v[100:103], v[172:175], v[196:199], v[100:103]
	v_mfma_f32_16x16x32_bf16 v[96:99], v[180:183], v[196:199], v[96:99]
	s_setprio 2
	s_barrier
	v_mfma_f32_16x16x32_bf16 v[84:87], v[172:175], v[204:207], v[84:87]
	v_mfma_f32_16x16x32_bf16 v[80:83], v[180:183], v[204:207], v[80:83]
	v_mfma_f32_16x16x32_bf16 v[68:71], v[172:175], v[212:215], v[68:71]
	v_mfma_f32_16x16x32_bf16 v[64:67], v[180:183], v[212:215], v[64:67]
	s_setprio 0
	s_add_i32 s66, s59, s47
	v_lshl_add_u64 v[160:161], s[38:39], 0, v[132:133]
	s_mov_b32 m0, s66
	ds_read_b128 v[184:187], v165 offset:16384
	ds_read_b128 v[188:191], v165 offset:17408
	ds_read_b128 v[192:195], v165 offset:18432
	ds_read_b128 v[196:199], v165 offset:19456
	ds_read_b128 v[200:203], v165 offset:20480
	ds_read_b128 v[204:207], v165 offset:21504
	ds_read_b128 v[208:211], v165 offset:22528
	ds_read_b128 v[212:215], v165 offset:23552
	global_load_lds_dwordx4 v[160:161], off
	s_add_i32 m0, s66, 0x2000
	s_add_u32 s66, s38, 0x40000
	v_lshl_add_u64 v[216:217], s[38:39], 0, v[128:129]
	s_addc_u32 s67, s39, 0
	s_add_i32 s68, s60, s47
	global_load_lds_dwordx4 v[216:217], off
	v_lshl_add_u64 v[218:219], s[66:67], 0, v[132:133]
	s_mov_b32 m0, s68
	v_lshl_add_u64 v[220:221], s[40:41], 0, v[130:131]
	global_load_lds_dwordx4 v[218:219], off
	v_lshl_add_u64 v[218:219], s[66:67], 0, v[128:129]
	s_add_i32 m0, s68, 0x2000
	s_nop 0
	global_load_lds_dwordx4 v[218:219], off
	v_lshl_add_u64 v[218:219], s[40:41], 0, v[134:135]
	s_mov_b32 m0, s50
	s_nop 0
	global_load_lds_dwordx4 v[218:219], off
	s_mov_b32 m0, s51
	s_nop 0
	global_load_lds_dwordx4 v[220:221], off
	s_waitcnt vmcnt(8)
	s_waitcnt lgkmcnt(0)
	s_barrier
	s_setprio 1
	s_waitcnt lgkmcnt(0)
	v_mfma_f32_16x16x32_bf16 v[60:63], v[144:147], v[184:187], v[60:63]
	v_mfma_f32_16x16x32_bf16 v[56:59], v[152:155], v[184:187], v[56:59]
	v_mfma_f32_16x16x32_bf16 v[44:47], v[144:147], v[192:195], v[44:47]
	v_mfma_f32_16x16x32_bf16 v[40:43], v[152:155], v[192:195], v[40:43]
	v_mfma_f32_16x16x32_bf16 v[28:31], v[144:147], v[200:203], v[28:31]
	v_mfma_f32_16x16x32_bf16 v[24:27], v[152:155], v[200:203], v[24:27]
	v_mfma_f32_16x16x32_bf16 v[12:15], v[144:147], v[208:211], v[12:15]
	v_mfma_f32_16x16x32_bf16 v[8:11], v[152:155], v[208:211], v[8:11]
	v_mfma_f32_16x16x32_bf16 v[60:63], v[148:151], v[188:191], v[60:63]
	v_mfma_f32_16x16x32_bf16 v[56:59], v[156:159], v[188:191], v[56:59]
	v_mfma_f32_16x16x32_bf16 v[44:47], v[148:151], v[196:199], v[44:47]
	v_mfma_f32_16x16x32_bf16 v[40:43], v[156:159], v[196:199], v[40:43]
	v_mfma_f32_16x16x32_bf16 v[28:31], v[148:151], v[204:207], v[28:31]
	v_mfma_f32_16x16x32_bf16 v[24:27], v[156:159], v[204:207], v[24:27]
	v_mfma_f32_16x16x32_bf16 v[12:15], v[148:151], v[212:215], v[12:15]
	v_mfma_f32_16x16x32_bf16 v[8:11], v[156:159], v[212:215], v[8:11]
	s_setprio 0
	s_setprio 1
	v_mfma_f32_16x16x32_bf16 v[52:55], v[168:171], v[184:187], v[52:55]
	v_mfma_f32_16x16x32_bf16 v[48:51], v[176:179], v[184:187], v[48:51]
	v_mfma_f32_16x16x32_bf16 v[36:39], v[168:171], v[192:195], v[36:39]
	v_mfma_f32_16x16x32_bf16 v[32:35], v[176:179], v[192:195], v[32:35]
	v_mfma_f32_16x16x32_bf16 v[20:23], v[168:171], v[200:203], v[20:23]
	v_mfma_f32_16x16x32_bf16 v[16:19], v[176:179], v[200:203], v[16:19]
	v_mfma_f32_16x16x32_bf16 v[4:7], v[168:171], v[208:211], v[4:7]
	v_mfma_f32_16x16x32_bf16 v[0:3], v[176:179], v[208:211], v[0:3]
	v_mfma_f32_16x16x32_bf16 v[52:55], v[172:175], v[188:191], v[52:55]
	v_mfma_f32_16x16x32_bf16 v[48:51], v[180:183], v[188:191], v[48:51]
	v_mfma_f32_16x16x32_bf16 v[36:39], v[172:175], v[196:199], v[36:39]
	v_mfma_f32_16x16x32_bf16 v[32:35], v[180:183], v[196:199], v[32:35]
	s_setprio 2
	s_barrier
	v_mfma_f32_16x16x32_bf16 v[20:23], v[172:175], v[204:207], v[20:23]
	v_mfma_f32_16x16x32_bf16 v[16:19], v[180:183], v[204:207], v[16:19]
	v_mfma_f32_16x16x32_bf16 v[4:7], v[172:175], v[212:215], v[4:7]
	v_mfma_f32_16x16x32_bf16 v[0:3], v[180:183], v[212:215], v[0:3]
	s_setprio 0
	s_add_i32 s66, 0, 0x18000
	s_add_i32 s67, 0, 0x1c000
	v_add_u32_e32 v156, s66, v162
	v_add_u32_e32 v167, s67, v162
	ds_read_b128 v[144:147], v156
	ds_read_b128 v[148:151], v156 offset:1024
	ds_read_b128 v[152:155], v156 offset:2048
	ds_read_b128 v[156:159], v156 offset:3072
	ds_read_b128 v[168:171], v167
	ds_read_b128 v[172:175], v167 offset:1024
	ds_read_b128 v[176:179], v167 offset:2048
	ds_read_b128 v[180:183], v167 offset:3072
	s_add_u32 s40, s40, 0x40000
	s_addc_u32 s41, s41, 0
	s_mov_b32 m0, s54
	v_lshl_add_u64 v[222:223], s[40:41], 0, v[134:135]
	ds_read_b128 v[184:187], v165 offset:32768
	ds_read_b128 v[188:191], v165 offset:33792
	ds_read_b128 v[192:195], v165 offset:34816
	ds_read_b128 v[196:199], v165 offset:35840
	ds_read_b128 v[200:203], v165 offset:36864
	ds_read_b128 v[204:207], v165 offset:37888
	ds_read_b128 v[208:211], v165 offset:38912
	ds_read_b128 v[212:215], v165 offset:39936
	global_load_lds_dwordx4 v[222:223], off
	v_lshl_add_u64 v[222:223], s[40:41], 0, v[130:131]
	s_mov_b32 m0, s55
	s_nop 0
	global_load_lds_dwordx4 v[222:223], off
	s_waitcnt vmcnt(8)
	s_waitcnt lgkmcnt(0)
	s_barrier
	s_setprio 1
	s_waitcnt lgkmcnt(0)
	v_mfma_f32_16x16x32_bf16 v[124:127], v[144:147], v[184:187], v[124:127]
	v_mfma_f32_16x16x32_bf16 v[120:123], v[152:155], v[184:187], v[120:123]
	v_mfma_f32_16x16x32_bf16 v[108:111], v[144:147], v[192:195], v[108:111]
	v_mfma_f32_16x16x32_bf16 v[104:107], v[152:155], v[192:195], v[104:107]
	v_mfma_f32_16x16x32_bf16 v[92:95], v[144:147], v[200:203], v[92:95]
	v_mfma_f32_16x16x32_bf16 v[88:91], v[152:155], v[200:203], v[88:91]
	v_mfma_f32_16x16x32_bf16 v[76:79], v[144:147], v[208:211], v[76:79]
	v_mfma_f32_16x16x32_bf16 v[72:75], v[152:155], v[208:211], v[72:75]
	v_mfma_f32_16x16x32_bf16 v[124:127], v[148:151], v[188:191], v[124:127]
	v_mfma_f32_16x16x32_bf16 v[120:123], v[156:159], v[188:191], v[120:123]
	v_mfma_f32_16x16x32_bf16 v[108:111], v[148:151], v[196:199], v[108:111]
	v_mfma_f32_16x16x32_bf16 v[104:107], v[156:159], v[196:199], v[104:107]
	v_mfma_f32_16x16x32_bf16 v[92:95], v[148:151], v[204:207], v[92:95]
	v_mfma_f32_16x16x32_bf16 v[88:91], v[156:159], v[204:207], v[88:91]
	v_mfma_f32_16x16x32_bf16 v[76:79], v[148:151], v[212:215], v[76:79]
	v_mfma_f32_16x16x32_bf16 v[72:75], v[156:159], v[212:215], v[72:75]
	s_setprio 0
	s_setprio 1
	v_mfma_f32_16x16x32_bf16 v[116:119], v[168:171], v[184:187], v[116:119]
	v_mfma_f32_16x16x32_bf16 v[112:115], v[176:179], v[184:187], v[112:115]
	v_mfma_f32_16x16x32_bf16 v[100:103], v[168:171], v[192:195], v[100:103]
	v_mfma_f32_16x16x32_bf16 v[96:99], v[176:179], v[192:195], v[96:99]
	v_mfma_f32_16x16x32_bf16 v[84:87], v[168:171], v[200:203], v[84:87]
	v_mfma_f32_16x16x32_bf16 v[80:83], v[176:179], v[200:203], v[80:83]
	v_mfma_f32_16x16x32_bf16 v[68:71], v[168:171], v[208:211], v[68:71]
	v_mfma_f32_16x16x32_bf16 v[64:67], v[176:179], v[208:211], v[64:67]
	v_mfma_f32_16x16x32_bf16 v[116:119], v[172:175], v[188:191], v[116:119]
	v_mfma_f32_16x16x32_bf16 v[112:115], v[180:183], v[188:191], v[112:115]
	v_mfma_f32_16x16x32_bf16 v[100:103], v[172:175], v[196:199], v[100:103]
	v_mfma_f32_16x16x32_bf16 v[96:99], v[180:183], v[196:199], v[96:99]
	s_setprio 2
	s_barrier
	v_mfma_f32_16x16x32_bf16 v[84:87], v[172:175], v[204:207], v[84:87]
	v_mfma_f32_16x16x32_bf16 v[80:83], v[180:183], v[204:207], v[80:83]
	v_mfma_f32_16x16x32_bf16 v[68:71], v[172:175], v[212:215], v[68:71]
	v_mfma_f32_16x16x32_bf16 v[64:67], v[180:183], v[212:215], v[64:67]
	s_setprio 0
	s_add_i32 s40, s66, s47
	v_lshl_add_u64 v[160:161], v[160:161], 0, s[16:17]
	s_mov_b32 m0, s40
	ds_read_b128 v[184:187], v165 offset:49152
	ds_read_b128 v[188:191], v165 offset:50176
	ds_read_b128 v[192:195], v165 offset:51200
	ds_read_b128 v[196:199], v165 offset:52224
	ds_read_b128 v[200:203], v165 offset:53248
	ds_read_b128 v[204:207], v165 offset:54272
	ds_read_b128 v[208:211], v165 offset:55296
	ds_read_b128 v[212:215], v165 offset:56320
	global_load_lds_dwordx4 v[160:161], off
	s_add_i32 m0, s40, 0x2000
	s_add_u32 s38, s38, 0x40080
	v_lshl_add_u64 v[160:161], v[216:217], 0, s[16:17]
	s_addc_u32 s39, s39, 0
	s_add_i32 s40, s67, s47
	global_load_lds_dwordx4 v[160:161], off
	v_lshl_add_u64 v[160:161], s[38:39], 0, v[132:133]
	s_mov_b32 m0, s40
	s_nop 0
	global_load_lds_dwordx4 v[160:161], off
	v_lshl_add_u64 v[160:161], s[38:39], 0, v[128:129]
	s_add_i32 m0, s40, 0x2000
	s_nop 0
	global_load_lds_dwordx4 v[160:161], off
	v_lshl_add_u64 v[160:161], v[218:219], 0, s[16:17]
	s_mov_b32 m0, s57
	s_nop 0
	global_load_lds_dwordx4 v[160:161], off
	v_lshl_add_u64 v[160:161], v[220:221], 0, s[16:17]
	s_mov_b32 m0, s58
	s_nop 0
	global_load_lds_dwordx4 v[160:161], off
	s_waitcnt vmcnt(8)
	s_waitcnt lgkmcnt(0)
	s_barrier
	s_setprio 1
	s_waitcnt lgkmcnt(0)
	v_mfma_f32_16x16x32_bf16 v[60:63], v[144:147], v[184:187], v[60:63]
	v_mfma_f32_16x16x32_bf16 v[56:59], v[152:155], v[184:187], v[56:59]
	v_mfma_f32_16x16x32_bf16 v[44:47], v[144:147], v[192:195], v[44:47]
	v_mfma_f32_16x16x32_bf16 v[40:43], v[152:155], v[192:195], v[40:43]
	v_mfma_f32_16x16x32_bf16 v[28:31], v[144:147], v[200:203], v[28:31]
	v_mfma_f32_16x16x32_bf16 v[24:27], v[152:155], v[200:203], v[24:27]
	v_mfma_f32_16x16x32_bf16 v[12:15], v[144:147], v[208:211], v[12:15]
	v_mfma_f32_16x16x32_bf16 v[8:11], v[152:155], v[208:211], v[8:11]
	v_mfma_f32_16x16x32_bf16 v[60:63], v[148:151], v[188:191], v[60:63]
	v_mfma_f32_16x16x32_bf16 v[56:59], v[156:159], v[188:191], v[56:59]
	v_mfma_f32_16x16x32_bf16 v[44:47], v[148:151], v[196:199], v[44:47]
	v_mfma_f32_16x16x32_bf16 v[40:43], v[156:159], v[196:199], v[40:43]
	v_mfma_f32_16x16x32_bf16 v[28:31], v[148:151], v[204:207], v[28:31]
	v_mfma_f32_16x16x32_bf16 v[24:27], v[156:159], v[204:207], v[24:27]
	v_mfma_f32_16x16x32_bf16 v[12:15], v[148:151], v[212:215], v[12:15]
	v_mfma_f32_16x16x32_bf16 v[8:11], v[156:159], v[212:215], v[8:11]
	s_setprio 0
	s_setprio 1
	v_mfma_f32_16x16x32_bf16 v[52:55], v[168:171], v[184:187], v[52:55]
	v_mfma_f32_16x16x32_bf16 v[48:51], v[176:179], v[184:187], v[48:51]
	v_mfma_f32_16x16x32_bf16 v[36:39], v[168:171], v[192:195], v[36:39]
	v_mfma_f32_16x16x32_bf16 v[32:35], v[176:179], v[192:195], v[32:35]
	v_mfma_f32_16x16x32_bf16 v[20:23], v[168:171], v[200:203], v[20:23]
	v_mfma_f32_16x16x32_bf16 v[16:19], v[176:179], v[200:203], v[16:19]
	v_mfma_f32_16x16x32_bf16 v[4:7], v[168:171], v[208:211], v[4:7]
	v_mfma_f32_16x16x32_bf16 v[0:3], v[176:179], v[208:211], v[0:3]
	v_mfma_f32_16x16x32_bf16 v[52:55], v[172:175], v[188:191], v[52:55]
	v_mfma_f32_16x16x32_bf16 v[48:51], v[180:183], v[188:191], v[48:51]
	v_mfma_f32_16x16x32_bf16 v[36:39], v[172:175], v[196:199], v[36:39]
	v_mfma_f32_16x16x32_bf16 v[32:35], v[180:183], v[196:199], v[32:35]
	s_setprio 2
	s_barrier
	v_mfma_f32_16x16x32_bf16 v[20:23], v[172:175], v[204:207], v[20:23]
	v_mfma_f32_16x16x32_bf16 v[16:19], v[180:183], v[204:207], v[16:19]
	v_mfma_f32_16x16x32_bf16 v[4:7], v[172:175], v[212:215], v[4:7]
	v_mfma_f32_16x16x32_bf16 v[0:3], v[180:183], v[212:215], v[0:3]
	s_setprio 0
	s_add_i32 s65, s65, 2
	s_add_u32 s36, s36, 0x100
	s_addc_u32 s37, s37, 0
	s_add_u32 s63, s63, 0x100
	s_addc_u32 s64, s64, 0
	s_cmp_gt_u32 s65, 13
	s_cbranch_scc0 .LBB0_784
	s_and_b64 vcc, exec, s[18:19]
	s_cbranch_vccz .LBB0_787
	s_barrier

.LBB0_866:
	ds_read_b128 v[120:123], v233
	ds_read_b128 v[124:127], v233 offset:1024
	ds_read_b128 v[136:139], v233 offset:2048
	ds_read_b128 v[140:143], v233 offset:3072
	ds_read_b128 v[144:147], v234
	ds_read_b128 v[148:151], v234 offset:1024
	ds_read_b128 v[152:155], v234 offset:2048
	ds_read_b128 v[156:159], v234 offset:3072
	s_add_u32 s28, s26, 0x100
	s_addc_u32 s29, s27, 0
	s_cmp_eq_u32 s64, 40
	s_cselect_b32 s37, s7, s29
	s_cselect_b32 s36, s6, s28
	s_cselect_b32 s31, s25, s63
	s_cselect_b32 s30, s24, s62
	v_lshl_add_u64 v[208:209], s[26:27], 0, v[192:193]
	s_add_i32 m0, s44, 0xc000
	ds_read_b128 v[160:163], v235
	ds_read_b128 v[164:167], v235 offset:1024
	ds_read_b128 v[168:171], v235 offset:2048
	ds_read_b128 v[172:175], v235 offset:3072
	ds_read_b128 v[176:179], v235 offset:4096
	ds_read_b128 v[180:183], v235 offset:5120
	ds_read_b128 v[200:203], v235 offset:6144
	ds_read_b128 v[204:207], v235 offset:7168
	global_load_lds_dwordx4 v[208:209], off
	v_lshl_add_u64 v[208:209], s[26:27], 0, v[194:195]
	s_add_i32 m0, s44, 0xe000
	s_nop 0
	global_load_lds_dwordx4 v[208:209], off
	s_waitcnt vmcnt(8)
	s_waitcnt lgkmcnt(0)
	s_barrier
	s_setprio 1
	s_waitcnt lgkmcnt(0)
	v_mfma_f32_16x16x32_bf16 v[132:135], v[120:123], v[160:163], v[132:135]
	v_mfma_f32_16x16x32_bf16 v[128:131], v[136:139], v[160:163], v[128:131]
	v_mfma_f32_16x16x32_bf16 v[108:111], v[120:123], v[168:171], v[108:111]
	v_mfma_f32_16x16x32_bf16 v[104:107], v[136:139], v[168:171], v[104:107]
	v_mfma_f32_16x16x32_bf16 v[92:95], v[120:123], v[176:179], v[92:95]
	v_mfma_f32_16x16x32_bf16 v[88:91], v[136:139], v[176:179], v[88:91]
	v_mfma_f32_16x16x32_bf16 v[76:79], v[120:123], v[200:203], v[76:79]
	v_mfma_f32_16x16x32_bf16 v[72:75], v[136:139], v[200:203], v[72:75]
	v_mfma_f32_16x16x32_bf16 v[132:135], v[124:127], v[164:167], v[132:135]
	v_mfma_f32_16x16x32_bf16 v[128:131], v[140:143], v[164:167], v[128:131]
	v_mfma_f32_16x16x32_bf16 v[108:111], v[124:127], v[172:175], v[108:111]
	v_mfma_f32_16x16x32_bf16 v[104:107], v[140:143], v[172:175], v[104:107]
	v_mfma_f32_16x16x32_bf16 v[92:95], v[124:127], v[180:183], v[92:95]
	v_mfma_f32_16x16x32_bf16 v[88:91], v[140:143], v[180:183], v[88:91]
	v_mfma_f32_16x16x32_bf16 v[76:79], v[124:127], v[204:207], v[76:79]
	v_mfma_f32_16x16x32_bf16 v[72:75], v[140:143], v[204:207], v[72:75]
	s_setprio 0
	s_setprio 1
	v_mfma_f32_16x16x32_bf16 v[116:119], v[144:147], v[160:163], v[116:119]
	v_mfma_f32_16x16x32_bf16 v[112:115], v[152:155], v[160:163], v[112:115]
	v_mfma_f32_16x16x32_bf16 v[100:103], v[144:147], v[168:171], v[100:103]
	v_mfma_f32_16x16x32_bf16 v[96:99], v[152:155], v[168:171], v[96:99]
	v_mfma_f32_16x16x32_bf16 v[84:87], v[144:147], v[176:179], v[84:87]
	v_mfma_f32_16x16x32_bf16 v[80:83], v[152:155], v[176:179], v[80:83]
	v_mfma_f32_16x16x32_bf16 v[68:71], v[144:147], v[200:203], v[68:71]
	v_mfma_f32_16x16x32_bf16 v[64:67], v[152:155], v[200:203], v[64:67]
	v_mfma_f32_16x16x32_bf16 v[116:119], v[148:151], v[164:167], v[116:119]
	v_mfma_f32_16x16x32_bf16 v[112:115], v[156:159], v[164:167], v[112:115]
	v_mfma_f32_16x16x32_bf16 v[100:103], v[148:151], v[172:175], v[100:103]
	v_mfma_f32_16x16x32_bf16 v[96:99], v[156:159], v[172:175], v[96:99]
	s_setprio 2
	s_barrier
	v_mfma_f32_16x16x32_bf16 v[84:87], v[148:151], v[180:183], v[84:87]
	v_mfma_f32_16x16x32_bf16 v[80:83], v[156:159], v[180:183], v[80:83]
	v_mfma_f32_16x16x32_bf16 v[68:71], v[148:151], v[204:207], v[68:71]
	v_mfma_f32_16x16x32_bf16 v[64:67], v[156:159], v[204:207], v[64:67]
	s_setprio 0
	s_add_i32 s26, s56, s43
	v_lshl_add_u64 v[208:209], s[30:31], 0, v[186:187]
	s_mov_b32 m0, s26
	ds_read_b128 v[160:163], v235 offset:16384
	ds_read_b128 v[164:167], v235 offset:17408
	ds_read_b128 v[168:171], v235 offset:18432
	ds_read_b128 v[172:175], v235 offset:19456
	ds_read_b128 v[176:179], v235 offset:20480
	ds_read_b128 v[180:183], v235 offset:21504
	ds_read_b128 v[200:203], v235 offset:22528
	ds_read_b128 v[204:207], v235 offset:23552
	global_load_lds_dwordx4 v[208:209], off
	s_add_i32 m0, s26, 0x2000
	s_add_u32 s26, s30, 0xb0000
	v_lshl_add_u64 v[210:211], s[30:31], 0, v[190:191]
	s_addc_u32 s27, s31, 0
	s_add_i32 s65, s57, s43
	global_load_lds_dwordx4 v[210:211], off
	v_lshl_add_u64 v[212:213], s[26:27], 0, v[186:187]
	s_mov_b32 m0, s65
	v_lshl_add_u64 v[214:215], s[36:37], 0, v[188:189]
	global_load_lds_dwordx4 v[212:213], off
	v_lshl_add_u64 v[212:213], s[26:27], 0, v[190:191]
	s_add_i32 m0, s65, 0x2000
	s_nop 0
	global_load_lds_dwordx4 v[212:213], off
	v_lshl_add_u64 v[212:213], s[36:37], 0, v[184:185]
	s_mov_b32 m0, s44
	s_nop 0
	global_load_lds_dwordx4 v[212:213], off
	s_mov_b32 m0, s45
	s_nop 0
	global_load_lds_dwordx4 v[214:215], off
	s_waitcnt vmcnt(8)
	s_waitcnt lgkmcnt(0)
	s_barrier
	s_setprio 1
	s_waitcnt lgkmcnt(0)
	v_mfma_f32_16x16x32_bf16 v[60:63], v[120:123], v[160:163], v[60:63]
	v_mfma_f32_16x16x32_bf16 v[56:59], v[136:139], v[160:163], v[56:59]
	v_mfma_f32_16x16x32_bf16 v[44:47], v[120:123], v[168:171], v[44:47]
	v_mfma_f32_16x16x32_bf16 v[40:43], v[136:139], v[168:171], v[40:43]
	v_mfma_f32_16x16x32_bf16 v[28:31], v[120:123], v[176:179], v[28:31]
	v_mfma_f32_16x16x32_bf16 v[24:27], v[136:139], v[176:179], v[24:27]
	v_mfma_f32_16x16x32_bf16 v[12:15], v[120:123], v[200:203], v[12:15]
	v_mfma_f32_16x16x32_bf16 v[8:11], v[136:139], v[200:203], v[8:11]
	v_mfma_f32_16x16x32_bf16 v[60:63], v[124:127], v[164:167], v[60:63]
	v_mfma_f32_16x16x32_bf16 v[56:59], v[140:143], v[164:167], v[56:59]
	v_mfma_f32_16x16x32_bf16 v[44:47], v[124:127], v[172:175], v[44:47]
	v_mfma_f32_16x16x32_bf16 v[40:43], v[140:143], v[172:175], v[40:43]
	v_mfma_f32_16x16x32_bf16 v[28:31], v[124:127], v[180:183], v[28:31]
	v_mfma_f32_16x16x32_bf16 v[24:27], v[140:143], v[180:183], v[24:27]
	v_mfma_f32_16x16x32_bf16 v[12:15], v[124:127], v[204:207], v[12:15]
	v_mfma_f32_16x16x32_bf16 v[8:11], v[140:143], v[204:207], v[8:11]
	s_setprio 0
	s_setprio 1
	v_mfma_f32_16x16x32_bf16 v[52:55], v[144:147], v[160:163], v[52:55]
	v_mfma_f32_16x16x32_bf16 v[48:51], v[152:155], v[160:163], v[48:51]
	v_mfma_f32_16x16x32_bf16 v[36:39], v[144:147], v[168:171], v[36:39]
	v_mfma_f32_16x16x32_bf16 v[32:35], v[152:155], v[168:171], v[32:35]
	v_mfma_f32_16x16x32_bf16 v[20:23], v[144:147], v[176:179], v[20:23]
	v_mfma_f32_16x16x32_bf16 v[16:19], v[152:155], v[176:179], v[16:19]
	v_mfma_f32_16x16x32_bf16 v[4:7], v[144:147], v[200:203], v[4:7]
	v_mfma_f32_16x16x32_bf16 v[0:3], v[152:155], v[200:203], v[0:3]
	v_mfma_f32_16x16x32_bf16 v[52:55], v[148:151], v[164:167], v[52:55]
	v_mfma_f32_16x16x32_bf16 v[48:51], v[156:159], v[164:167], v[48:51]
	v_mfma_f32_16x16x32_bf16 v[36:39], v[148:151], v[172:175], v[36:39]
	v_mfma_f32_16x16x32_bf16 v[32:35], v[156:159], v[172:175], v[32:35]
	s_setprio 2
	s_barrier
	v_mfma_f32_16x16x32_bf16 v[20:23], v[148:151], v[180:183], v[20:23]
	v_mfma_f32_16x16x32_bf16 v[16:19], v[156:159], v[180:183], v[16:19]
	v_mfma_f32_16x16x32_bf16 v[4:7], v[148:151], v[204:207], v[4:7]
	v_mfma_f32_16x16x32_bf16 v[0:3], v[156:159], v[204:207], v[0:3]
	s_setprio 0
	s_add_i32 s65, 0, 0x18000
	s_add_i32 s66, 0, 0x1c000
	v_add_u32_e32 v140, s65, v232
	v_add_u32_e32 v156, s66, v232
	ds_read_b128 v[120:123], v140
	ds_read_b128 v[124:127], v140 offset:1024
	ds_read_b128 v[136:139], v140 offset:2048
	ds_read_b128 v[140:143], v140 offset:3072
	ds_read_b128 v[144:147], v156
	ds_read_b128 v[148:151], v156 offset:1024
	ds_read_b128 v[152:155], v156 offset:2048
	ds_read_b128 v[156:159], v156 offset:3072
	s_add_u32 s26, s36, 0xb0000
	s_addc_u32 s27, s37, 0
	s_mov_b32 m0, s46
	v_lshl_add_u64 v[216:217], s[26:27], 0, v[184:185]
	ds_read_b128 v[160:163], v235 offset:32768
	ds_read_b128 v[164:167], v235 offset:33792
	ds_read_b128 v[168:171], v235 offset:34816
	ds_read_b128 v[172:175], v235 offset:35840
	ds_read_b128 v[176:179], v235 offset:36864
	ds_read_b128 v[180:183], v235 offset:37888
	ds_read_b128 v[200:203], v235 offset:38912
	ds_read_b128 v[204:207], v235 offset:39936
	global_load_lds_dwordx4 v[216:217], off
	v_lshl_add_u64 v[216:217], s[26:27], 0, v[188:189]
	s_mov_b32 m0, s47
	s_nop 0
	global_load_lds_dwordx4 v[216:217], off
	s_waitcnt vmcnt(8)
	s_waitcnt lgkmcnt(0)
	s_barrier
	s_setprio 1
	s_waitcnt lgkmcnt(0)
	v_mfma_f32_16x16x32_bf16 v[132:135], v[120:123], v[160:163], v[132:135]
	v_mfma_f32_16x16x32_bf16 v[128:131], v[136:139], v[160:163], v[128:131]
	v_mfma_f32_16x16x32_bf16 v[108:111], v[120:123], v[168:171], v[108:111]
	v_mfma_f32_16x16x32_bf16 v[104:107], v[136:139], v[168:171], v[104:107]
	v_mfma_f32_16x16x32_bf16 v[92:95], v[120:123], v[176:179], v[92:95]
	v_mfma_f32_16x16x32_bf16 v[88:91], v[136:139], v[176:179], v[88:91]
	v_mfma_f32_16x16x32_bf16 v[76:79], v[120:123], v[200:203], v[76:79]
	v_mfma_f32_16x16x32_bf16 v[72:75], v[136:139], v[200:203], v[72:75]
	v_mfma_f32_16x16x32_bf16 v[132:135], v[124:127], v[164:167], v[132:135]
	v_mfma_f32_16x16x32_bf16 v[128:131], v[140:143], v[164:167], v[128:131]
	v_mfma_f32_16x16x32_bf16 v[108:111], v[124:127], v[172:175], v[108:111]
	v_mfma_f32_16x16x32_bf16 v[104:107], v[140:143], v[172:175], v[104:107]
	v_mfma_f32_16x16x32_bf16 v[92:95], v[124:127], v[180:183], v[92:95]
	v_mfma_f32_16x16x32_bf16 v[88:91], v[140:143], v[180:183], v[88:91]
	v_mfma_f32_16x16x32_bf16 v[76:79], v[124:127], v[204:207], v[76:79]
	v_mfma_f32_16x16x32_bf16 v[72:75], v[140:143], v[204:207], v[72:75]
	s_setprio 0
	s_setprio 1
	v_mfma_f32_16x16x32_bf16 v[116:119], v[144:147], v[160:163], v[116:119]
	v_mfma_f32_16x16x32_bf16 v[112:115], v[152:155], v[160:163], v[112:115]
	v_mfma_f32_16x16x32_bf16 v[100:103], v[144:147], v[168:171], v[100:103]
	v_mfma_f32_16x16x32_bf16 v[96:99], v[152:155], v[168:171], v[96:99]
	v_mfma_f32_16x16x32_bf16 v[84:87], v[144:147], v[176:179], v[84:87]
	v_mfma_f32_16x16x32_bf16 v[80:83], v[152:155], v[176:179], v[80:83]
	v_mfma_f32_16x16x32_bf16 v[68:71], v[144:147], v[200:203], v[68:71]
	v_mfma_f32_16x16x32_bf16 v[64:67], v[152:155], v[200:203], v[64:67]
	v_mfma_f32_16x16x32_bf16 v[116:119], v[148:151], v[164:167], v[116:119]
	v_mfma_f32_16x16x32_bf16 v[112:115], v[156:159], v[164:167], v[112:115]
	v_mfma_f32_16x16x32_bf16 v[100:103], v[148:151], v[172:175], v[100:103]
	v_mfma_f32_16x16x32_bf16 v[96:99], v[156:159], v[172:175], v[96:99]
	s_setprio 2
	s_barrier
	v_mfma_f32_16x16x32_bf16 v[84:87], v[148:151], v[180:183], v[84:87]
	v_mfma_f32_16x16x32_bf16 v[80:83], v[156:159], v[180:183], v[80:83]
	v_mfma_f32_16x16x32_bf16 v[68:71], v[148:151], v[204:207], v[68:71]
	v_mfma_f32_16x16x32_bf16 v[64:67], v[156:159], v[204:207], v[64:67]
	s_setprio 0
	s_add_i32 s26, s65, s43
	v_lshl_add_u64 v[208:209], v[208:209], 0, s[20:21]
	s_mov_b32 m0, s26
	ds_read_b128 v[160:163], v235 offset:49152
	ds_read_b128 v[164:167], v235 offset:50176
	ds_read_b128 v[168:171], v235 offset:51200
	ds_read_b128 v[172:175], v235 offset:52224
	ds_read_b128 v[176:179], v235 offset:53248
	ds_read_b128 v[180:183], v235 offset:54272
	ds_read_b128 v[200:203], v235 offset:55296
	ds_read_b128 v[204:207], v235 offset:56320
	global_load_lds_dwordx4 v[208:209], off
	s_add_i32 m0, s26, 0x2000
	s_add_u32 s26, s30, 0xb0080
	v_lshl_add_u64 v[208:209], v[210:211], 0, s[20:21]
	s_addc_u32 s27, s31, 0
	s_add_i32 s30, s66, s43
	global_load_lds_dwordx4 v[208:209], off
	v_lshl_add_u64 v[208:209], s[26:27], 0, v[186:187]
	s_mov_b32 m0, s30
	s_nop 0
	global_load_lds_dwordx4 v[208:209], off
	v_lshl_add_u64 v[208:209], s[26:27], 0, v[190:191]
	s_add_i32 m0, s30, 0x2000
	s_nop 0
	global_load_lds_dwordx4 v[208:209], off
	v_lshl_add_u64 v[208:209], v[212:213], 0, s[20:21]
	s_mov_b32 m0, s49
	s_nop 0
	global_load_lds_dwordx4 v[208:209], off
	v_lshl_add_u64 v[208:209], v[214:215], 0, s[20:21]
	s_mov_b32 m0, s50
	s_nop 0
	global_load_lds_dwordx4 v[208:209], off
	s_waitcnt vmcnt(8)
	s_waitcnt lgkmcnt(0)
	s_barrier
	s_setprio 1
	s_waitcnt lgkmcnt(0)
	v_mfma_f32_16x16x32_bf16 v[60:63], v[120:123], v[160:163], v[60:63]
	v_mfma_f32_16x16x32_bf16 v[56:59], v[136:139], v[160:163], v[56:59]
	v_mfma_f32_16x16x32_bf16 v[44:47], v[120:123], v[168:171], v[44:47]
	v_mfma_f32_16x16x32_bf16 v[40:43], v[136:139], v[168:171], v[40:43]
	v_mfma_f32_16x16x32_bf16 v[28:31], v[120:123], v[176:179], v[28:31]
	v_mfma_f32_16x16x32_bf16 v[24:27], v[136:139], v[176:179], v[24:27]
	v_mfma_f32_16x16x32_bf16 v[12:15], v[120:123], v[200:203], v[12:15]
	v_mfma_f32_16x16x32_bf16 v[8:11], v[136:139], v[200:203], v[8:11]
	v_mfma_f32_16x16x32_bf16 v[60:63], v[124:127], v[164:167], v[60:63]
	v_mfma_f32_16x16x32_bf16 v[56:59], v[140:143], v[164:167], v[56:59]
	v_mfma_f32_16x16x32_bf16 v[44:47], v[124:127], v[172:175], v[44:47]
	v_mfma_f32_16x16x32_bf16 v[40:43], v[140:143], v[172:175], v[40:43]
	v_mfma_f32_16x16x32_bf16 v[28:31], v[124:127], v[180:183], v[28:31]
	v_mfma_f32_16x16x32_bf16 v[24:27], v[140:143], v[180:183], v[24:27]
	v_mfma_f32_16x16x32_bf16 v[12:15], v[124:127], v[204:207], v[12:15]
	v_mfma_f32_16x16x32_bf16 v[8:11], v[140:143], v[204:207], v[8:11]
	s_setprio 0
	s_setprio 1
	v_mfma_f32_16x16x32_bf16 v[52:55], v[144:147], v[160:163], v[52:55]
	v_mfma_f32_16x16x32_bf16 v[48:51], v[152:155], v[160:163], v[48:51]
	v_mfma_f32_16x16x32_bf16 v[36:39], v[144:147], v[168:171], v[36:39]
	v_mfma_f32_16x16x32_bf16 v[32:35], v[152:155], v[168:171], v[32:35]
	v_mfma_f32_16x16x32_bf16 v[20:23], v[144:147], v[176:179], v[20:23]
	v_mfma_f32_16x16x32_bf16 v[16:19], v[152:155], v[176:179], v[16:19]
	v_mfma_f32_16x16x32_bf16 v[4:7], v[144:147], v[200:203], v[4:7]
	v_mfma_f32_16x16x32_bf16 v[0:3], v[152:155], v[200:203], v[0:3]
	v_mfma_f32_16x16x32_bf16 v[52:55], v[148:151], v[164:167], v[52:55]
	v_mfma_f32_16x16x32_bf16 v[48:51], v[156:159], v[164:167], v[48:51]
	v_mfma_f32_16x16x32_bf16 v[36:39], v[148:151], v[172:175], v[36:39]
	v_mfma_f32_16x16x32_bf16 v[32:35], v[156:159], v[172:175], v[32:35]
	s_setprio 2
	s_barrier
	v_mfma_f32_16x16x32_bf16 v[20:23], v[148:151], v[180:183], v[20:23]
	v_mfma_f32_16x16x32_bf16 v[16:19], v[156:159], v[180:183], v[16:19]
	v_mfma_f32_16x16x32_bf16 v[4:7], v[148:151], v[204:207], v[4:7]
	v_mfma_f32_16x16x32_bf16 v[0:3], v[156:159], v[204:207], v[0:3]
	s_setprio 0
	s_add_i32 s64, s64, 2
	s_add_u32 s62, s62, 0x100
	s_addc_u32 s63, s63, 0
	s_cmp_gt_u32 s64, 41
	s_mov_b64 s[26:27], s[28:29]
	s_cbranch_scc0 .LBB0_866
	s_and_b64 vcc, exec, s[22:23]
	s_cbranch_vccz .LBB0_869
	s_barrier

.LBB0_952:
	ds_read_b128 v[144:147], v179
	ds_read_b128 v[148:151], v179 offset:1024
	ds_read_b128 v[152:155], v179 offset:2048
	ds_read_b128 v[156:159], v179 offset:3072
	ds_read_b128 v[160:163], v180
	ds_read_b128 v[164:167], v180 offset:1024
	ds_read_b128 v[168:171], v180 offset:2048
	ds_read_b128 v[172:175], v180 offset:3072
	s_add_u32 s40, s6, 0xfffc0080
	s_addc_u32 s41, s7, -1
	s_cmp_eq_u32 s73, 12
	s_cselect_b32 s45, s27, s41
	s_cselect_b32 s44, s39, s40
	s_cselect_b32 s41, s29, s72
	s_cselect_b32 s40, s43, s71
	v_lshl_add_u64 v[176:177], s[6:7], 0, v[136:137]
	s_add_i32 m0, s54, 0xc000
	ds_read_b128 v[184:187], v181
	ds_read_b128 v[188:191], v181 offset:1024
	ds_read_b128 v[192:195], v181 offset:2048
	ds_read_b128 v[196:199], v181 offset:3072
	ds_read_b128 v[200:203], v181 offset:4096
	ds_read_b128 v[204:207], v181 offset:5120
	ds_read_b128 v[208:211], v181 offset:6144
	ds_read_b128 v[212:215], v181 offset:7168
	global_load_lds_dwordx4 v[176:177], off
	v_lshl_add_u64 v[176:177], s[6:7], 0, v[138:139]
	s_add_i32 m0, s54, 0xe000
	s_nop 0
	global_load_lds_dwordx4 v[176:177], off
	s_waitcnt vmcnt(8)
	s_waitcnt lgkmcnt(0)
	s_barrier
	s_setprio 1
	s_waitcnt lgkmcnt(0)
	v_mfma_f32_16x16x32_bf16 v[124:127], v[144:147], v[184:187], v[124:127]
	v_mfma_f32_16x16x32_bf16 v[120:123], v[152:155], v[184:187], v[120:123]
	v_mfma_f32_16x16x32_bf16 v[108:111], v[144:147], v[192:195], v[108:111]
	v_mfma_f32_16x16x32_bf16 v[104:107], v[152:155], v[192:195], v[104:107]
	v_mfma_f32_16x16x32_bf16 v[92:95], v[144:147], v[200:203], v[92:95]
	v_mfma_f32_16x16x32_bf16 v[88:91], v[152:155], v[200:203], v[88:91]
	v_mfma_f32_16x16x32_bf16 v[76:79], v[144:147], v[208:211], v[76:79]
	v_mfma_f32_16x16x32_bf16 v[72:75], v[152:155], v[208:211], v[72:75]
	v_mfma_f32_16x16x32_bf16 v[124:127], v[148:151], v[188:191], v[124:127]
	v_mfma_f32_16x16x32_bf16 v[120:123], v[156:159], v[188:191], v[120:123]
	v_mfma_f32_16x16x32_bf16 v[108:111], v[148:151], v[196:199], v[108:111]
	v_mfma_f32_16x16x32_bf16 v[104:107], v[156:159], v[196:199], v[104:107]
	v_mfma_f32_16x16x32_bf16 v[92:95], v[148:151], v[204:207], v[92:95]
	v_mfma_f32_16x16x32_bf16 v[88:91], v[156:159], v[204:207], v[88:91]
	v_mfma_f32_16x16x32_bf16 v[76:79], v[148:151], v[212:215], v[76:79]
	v_mfma_f32_16x16x32_bf16 v[72:75], v[156:159], v[212:215], v[72:75]
	s_setprio 0
	s_setprio 1
	v_mfma_f32_16x16x32_bf16 v[116:119], v[160:163], v[184:187], v[116:119]
	v_mfma_f32_16x16x32_bf16 v[112:115], v[168:171], v[184:187], v[112:115]
	v_mfma_f32_16x16x32_bf16 v[100:103], v[160:163], v[192:195], v[100:103]
	v_mfma_f32_16x16x32_bf16 v[96:99], v[168:171], v[192:195], v[96:99]
	v_mfma_f32_16x16x32_bf16 v[84:87], v[160:163], v[200:203], v[84:87]
	v_mfma_f32_16x16x32_bf16 v[80:83], v[168:171], v[200:203], v[80:83]
	v_mfma_f32_16x16x32_bf16 v[68:71], v[160:163], v[208:211], v[68:71]
	v_mfma_f32_16x16x32_bf16 v[64:67], v[168:171], v[208:211], v[64:67]
	v_mfma_f32_16x16x32_bf16 v[116:119], v[164:167], v[188:191], v[116:119]
	v_mfma_f32_16x16x32_bf16 v[112:115], v[172:175], v[188:191], v[112:115]
	v_mfma_f32_16x16x32_bf16 v[100:103], v[164:167], v[196:199], v[100:103]
	v_mfma_f32_16x16x32_bf16 v[96:99], v[172:175], v[196:199], v[96:99]
	s_setprio 2
	s_barrier
	v_mfma_f32_16x16x32_bf16 v[84:87], v[164:167], v[204:207], v[84:87]
	v_mfma_f32_16x16x32_bf16 v[80:83], v[172:175], v[204:207], v[80:83]
	v_mfma_f32_16x16x32_bf16 v[68:71], v[164:167], v[212:215], v[68:71]
	v_mfma_f32_16x16x32_bf16 v[64:67], v[172:175], v[212:215], v[64:67]
	s_setprio 0
	s_add_i32 s74, s69, s51
	v_lshl_add_u64 v[176:177], s[40:41], 0, v[130:131]
	s_mov_b32 m0, s74
	ds_read_b128 v[184:187], v181 offset:16384
	ds_read_b128 v[188:191], v181 offset:17408
	ds_read_b128 v[192:195], v181 offset:18432
	ds_read_b128 v[196:199], v181 offset:19456
	ds_read_b128 v[200:203], v181 offset:20480
	ds_read_b128 v[204:207], v181 offset:21504
	ds_read_b128 v[208:211], v181 offset:22528
	ds_read_b128 v[212:215], v181 offset:23552
	global_load_lds_dwordx4 v[176:177], off
	s_add_i32 m0, s74, 0x2000
	s_add_u32 s74, s40, 0x40000
	v_lshl_add_u64 v[216:217], s[40:41], 0, v[134:135]
	s_addc_u32 s75, s41, 0
	s_add_i32 s76, s70, s51
	global_load_lds_dwordx4 v[216:217], off
	v_lshl_add_u64 v[218:219], s[74:75], 0, v[130:131]
	s_mov_b32 m0, s76
	v_lshl_add_u64 v[220:221], s[44:45], 0, v[132:133]
	global_load_lds_dwordx4 v[218:219], off
	v_lshl_add_u64 v[218:219], s[74:75], 0, v[134:135]
	s_add_i32 m0, s76, 0x2000
	s_nop 0
	global_load_lds_dwordx4 v[218:219], off
	v_lshl_add_u64 v[218:219], s[44:45], 0, v[128:129]
	s_mov_b32 m0, s54
	s_nop 0
	global_load_lds_dwordx4 v[218:219], off
	s_mov_b32 m0, s55
	s_nop 0
	global_load_lds_dwordx4 v[220:221], off
	s_waitcnt vmcnt(8)
	s_waitcnt lgkmcnt(0)
	s_barrier
	s_setprio 1
	s_waitcnt lgkmcnt(0)
	v_mfma_f32_16x16x32_bf16 v[60:63], v[144:147], v[184:187], v[60:63]
	v_mfma_f32_16x16x32_bf16 v[56:59], v[152:155], v[184:187], v[56:59]
	v_mfma_f32_16x16x32_bf16 v[44:47], v[144:147], v[192:195], v[44:47]
	v_mfma_f32_16x16x32_bf16 v[40:43], v[152:155], v[192:195], v[40:43]
	v_mfma_f32_16x16x32_bf16 v[28:31], v[144:147], v[200:203], v[28:31]
	v_mfma_f32_16x16x32_bf16 v[24:27], v[152:155], v[200:203], v[24:27]
	v_mfma_f32_16x16x32_bf16 v[12:15], v[144:147], v[208:211], v[12:15]
	v_mfma_f32_16x16x32_bf16 v[8:11], v[152:155], v[208:211], v[8:11]
	v_mfma_f32_16x16x32_bf16 v[60:63], v[148:151], v[188:191], v[60:63]
	v_mfma_f32_16x16x32_bf16 v[56:59], v[156:159], v[188:191], v[56:59]
	v_mfma_f32_16x16x32_bf16 v[44:47], v[148:151], v[196:199], v[44:47]
	v_mfma_f32_16x16x32_bf16 v[40:43], v[156:159], v[196:199], v[40:43]
	v_mfma_f32_16x16x32_bf16 v[28:31], v[148:151], v[204:207], v[28:31]
	v_mfma_f32_16x16x32_bf16 v[24:27], v[156:159], v[204:207], v[24:27]
	v_mfma_f32_16x16x32_bf16 v[12:15], v[148:151], v[212:215], v[12:15]
	v_mfma_f32_16x16x32_bf16 v[8:11], v[156:159], v[212:215], v[8:11]
	s_setprio 0
	s_setprio 1
	v_mfma_f32_16x16x32_bf16 v[52:55], v[160:163], v[184:187], v[52:55]
	v_mfma_f32_16x16x32_bf16 v[48:51], v[168:171], v[184:187], v[48:51]
	v_mfma_f32_16x16x32_bf16 v[36:39], v[160:163], v[192:195], v[36:39]
	v_mfma_f32_16x16x32_bf16 v[32:35], v[168:171], v[192:195], v[32:35]
	v_mfma_f32_16x16x32_bf16 v[20:23], v[160:163], v[200:203], v[20:23]
	v_mfma_f32_16x16x32_bf16 v[16:19], v[168:171], v[200:203], v[16:19]
	v_mfma_f32_16x16x32_bf16 v[4:7], v[160:163], v[208:211], v[4:7]
	v_mfma_f32_16x16x32_bf16 v[0:3], v[168:171], v[208:211], v[0:3]
	v_mfma_f32_16x16x32_bf16 v[52:55], v[164:167], v[188:191], v[52:55]
	v_mfma_f32_16x16x32_bf16 v[48:51], v[172:175], v[188:191], v[48:51]
	v_mfma_f32_16x16x32_bf16 v[36:39], v[164:167], v[196:199], v[36:39]
	v_mfma_f32_16x16x32_bf16 v[32:35], v[172:175], v[196:199], v[32:35]
	s_setprio 2
	s_barrier
	v_mfma_f32_16x16x32_bf16 v[20:23], v[164:167], v[204:207], v[20:23]
	v_mfma_f32_16x16x32_bf16 v[16:19], v[172:175], v[204:207], v[16:19]
	v_mfma_f32_16x16x32_bf16 v[4:7], v[164:167], v[212:215], v[4:7]
	v_mfma_f32_16x16x32_bf16 v[0:3], v[172:175], v[212:215], v[0:3]
	s_setprio 0
	s_add_i32 s74, 0, 0x18000
	s_add_i32 s75, 0, 0x1c000
	v_add_u32_e32 v156, s74, v178
	v_add_u32_e32 v172, s75, v178
	ds_read_b128 v[144:147], v156
	ds_read_b128 v[148:151], v156 offset:1024
	ds_read_b128 v[152:155], v156 offset:2048
	ds_read_b128 v[156:159], v156 offset:3072
	ds_read_b128 v[160:163], v172
	ds_read_b128 v[164:167], v172 offset:1024
	ds_read_b128 v[168:171], v172 offset:2048
	ds_read_b128 v[172:175], v172 offset:3072
	s_add_u32 s44, s44, 0x40000
	s_addc_u32 s45, s45, 0
	s_mov_b32 m0, s56
	v_lshl_add_u64 v[222:223], s[44:45], 0, v[128:129]
	ds_read_b128 v[184:187], v181 offset:32768
	ds_read_b128 v[188:191], v181 offset:33792
	ds_read_b128 v[192:195], v181 offset:34816
	ds_read_b128 v[196:199], v181 offset:35840
	ds_read_b128 v[200:203], v181 offset:36864
	ds_read_b128 v[204:207], v181 offset:37888
	ds_read_b128 v[208:211], v181 offset:38912
	ds_read_b128 v[212:215], v181 offset:39936
	global_load_lds_dwordx4 v[222:223], off
	v_lshl_add_u64 v[222:223], s[44:45], 0, v[132:133]
	s_mov_b32 m0, s57
	s_nop 0
	global_load_lds_dwordx4 v[222:223], off
	s_waitcnt vmcnt(8)
	s_waitcnt lgkmcnt(0)
	s_barrier
	s_setprio 1
	s_waitcnt lgkmcnt(0)
	v_mfma_f32_16x16x32_bf16 v[124:127], v[144:147], v[184:187], v[124:127]
	v_mfma_f32_16x16x32_bf16 v[120:123], v[152:155], v[184:187], v[120:123]
	v_mfma_f32_16x16x32_bf16 v[108:111], v[144:147], v[192:195], v[108:111]
	v_mfma_f32_16x16x32_bf16 v[104:107], v[152:155], v[192:195], v[104:107]
	v_mfma_f32_16x16x32_bf16 v[92:95], v[144:147], v[200:203], v[92:95]
	v_mfma_f32_16x16x32_bf16 v[88:91], v[152:155], v[200:203], v[88:91]
	v_mfma_f32_16x16x32_bf16 v[76:79], v[144:147], v[208:211], v[76:79]
	v_mfma_f32_16x16x32_bf16 v[72:75], v[152:155], v[208:211], v[72:75]
	v_mfma_f32_16x16x32_bf16 v[124:127], v[148:151], v[188:191], v[124:127]
	v_mfma_f32_16x16x32_bf16 v[120:123], v[156:159], v[188:191], v[120:123]
	v_mfma_f32_16x16x32_bf16 v[108:111], v[148:151], v[196:199], v[108:111]
	v_mfma_f32_16x16x32_bf16 v[104:107], v[156:159], v[196:199], v[104:107]
	v_mfma_f32_16x16x32_bf16 v[92:95], v[148:151], v[204:207], v[92:95]
	v_mfma_f32_16x16x32_bf16 v[88:91], v[156:159], v[204:207], v[88:91]
	v_mfma_f32_16x16x32_bf16 v[76:79], v[148:151], v[212:215], v[76:79]
	v_mfma_f32_16x16x32_bf16 v[72:75], v[156:159], v[212:215], v[72:75]
	s_setprio 0
	s_setprio 1
	v_mfma_f32_16x16x32_bf16 v[116:119], v[160:163], v[184:187], v[116:119]
	v_mfma_f32_16x16x32_bf16 v[112:115], v[168:171], v[184:187], v[112:115]
	v_mfma_f32_16x16x32_bf16 v[100:103], v[160:163], v[192:195], v[100:103]
	v_mfma_f32_16x16x32_bf16 v[96:99], v[168:171], v[192:195], v[96:99]
	v_mfma_f32_16x16x32_bf16 v[84:87], v[160:163], v[200:203], v[84:87]
	v_mfma_f32_16x16x32_bf16 v[80:83], v[168:171], v[200:203], v[80:83]
	v_mfma_f32_16x16x32_bf16 v[68:71], v[160:163], v[208:211], v[68:71]
	v_mfma_f32_16x16x32_bf16 v[64:67], v[168:171], v[208:211], v[64:67]
	v_mfma_f32_16x16x32_bf16 v[116:119], v[164:167], v[188:191], v[116:119]
	v_mfma_f32_16x16x32_bf16 v[112:115], v[172:175], v[188:191], v[112:115]
	v_mfma_f32_16x16x32_bf16 v[100:103], v[164:167], v[196:199], v[100:103]
	v_mfma_f32_16x16x32_bf16 v[96:99], v[172:175], v[196:199], v[96:99]
	s_setprio 2
	s_barrier
	v_mfma_f32_16x16x32_bf16 v[84:87], v[164:167], v[204:207], v[84:87]
	v_mfma_f32_16x16x32_bf16 v[80:83], v[172:175], v[204:207], v[80:83]
	v_mfma_f32_16x16x32_bf16 v[68:71], v[164:167], v[212:215], v[68:71]
	v_mfma_f32_16x16x32_bf16 v[64:67], v[172:175], v[212:215], v[64:67]
	s_setprio 0
	s_add_i32 s44, s74, s51
	v_lshl_add_u64 v[176:177], v[176:177], 0, s[22:23]
	s_mov_b32 m0, s44
	ds_read_b128 v[184:187], v181 offset:49152
	ds_read_b128 v[188:191], v181 offset:50176
	ds_read_b128 v[192:195], v181 offset:51200
	ds_read_b128 v[196:199], v181 offset:52224
	ds_read_b128 v[200:203], v181 offset:53248
	ds_read_b128 v[204:207], v181 offset:54272
	ds_read_b128 v[208:211], v181 offset:55296
	ds_read_b128 v[212:215], v181 offset:56320
	global_load_lds_dwordx4 v[176:177], off
	s_add_i32 m0, s44, 0x2000
	s_add_u32 s40, s40, 0x40080
	v_lshl_add_u64 v[176:177], v[216:217], 0, s[22:23]
	s_addc_u32 s41, s41, 0
	s_add_i32 s44, s75, s51
	global_load_lds_dwordx4 v[176:177], off
	v_lshl_add_u64 v[176:177], s[40:41], 0, v[130:131]
	s_mov_b32 m0, s44
	s_nop 0
	global_load_lds_dwordx4 v[176:177], off
	v_lshl_add_u64 v[176:177], s[40:41], 0, v[134:135]
	s_add_i32 m0, s44, 0x2000
	s_nop 0
	global_load_lds_dwordx4 v[176:177], off
	v_lshl_add_u64 v[176:177], v[218:219], 0, s[22:23]
	s_mov_b32 m0, s64
	s_nop 0
	global_load_lds_dwordx4 v[176:177], off
	v_lshl_add_u64 v[176:177], v[220:221], 0, s[22:23]
	s_mov_b32 m0, s65
	s_nop 0
	global_load_lds_dwordx4 v[176:177], off
	s_waitcnt vmcnt(8)
	s_waitcnt lgkmcnt(0)
	s_barrier
	s_setprio 1
	s_waitcnt lgkmcnt(0)
	v_mfma_f32_16x16x32_bf16 v[60:63], v[144:147], v[184:187], v[60:63]
	v_mfma_f32_16x16x32_bf16 v[56:59], v[152:155], v[184:187], v[56:59]
	v_mfma_f32_16x16x32_bf16 v[44:47], v[144:147], v[192:195], v[44:47]
	v_mfma_f32_16x16x32_bf16 v[40:43], v[152:155], v[192:195], v[40:43]
	v_mfma_f32_16x16x32_bf16 v[28:31], v[144:147], v[200:203], v[28:31]
	v_mfma_f32_16x16x32_bf16 v[24:27], v[152:155], v[200:203], v[24:27]
	v_mfma_f32_16x16x32_bf16 v[12:15], v[144:147], v[208:211], v[12:15]
	v_mfma_f32_16x16x32_bf16 v[8:11], v[152:155], v[208:211], v[8:11]
	v_mfma_f32_16x16x32_bf16 v[60:63], v[148:151], v[188:191], v[60:63]
	v_mfma_f32_16x16x32_bf16 v[56:59], v[156:159], v[188:191], v[56:59]
	v_mfma_f32_16x16x32_bf16 v[44:47], v[148:151], v[196:199], v[44:47]
	v_mfma_f32_16x16x32_bf16 v[40:43], v[156:159], v[196:199], v[40:43]
	v_mfma_f32_16x16x32_bf16 v[28:31], v[148:151], v[204:207], v[28:31]
	v_mfma_f32_16x16x32_bf16 v[24:27], v[156:159], v[204:207], v[24:27]
	v_mfma_f32_16x16x32_bf16 v[12:15], v[148:151], v[212:215], v[12:15]
	v_mfma_f32_16x16x32_bf16 v[8:11], v[156:159], v[212:215], v[8:11]
	s_setprio 0
	s_setprio 1
	v_mfma_f32_16x16x32_bf16 v[52:55], v[160:163], v[184:187], v[52:55]
	v_mfma_f32_16x16x32_bf16 v[48:51], v[168:171], v[184:187], v[48:51]
	v_mfma_f32_16x16x32_bf16 v[36:39], v[160:163], v[192:195], v[36:39]
	v_mfma_f32_16x16x32_bf16 v[32:35], v[168:171], v[192:195], v[32:35]
	v_mfma_f32_16x16x32_bf16 v[20:23], v[160:163], v[200:203], v[20:23]
	v_mfma_f32_16x16x32_bf16 v[16:19], v[168:171], v[200:203], v[16:19]
	v_mfma_f32_16x16x32_bf16 v[4:7], v[160:163], v[208:211], v[4:7]
	v_mfma_f32_16x16x32_bf16 v[0:3], v[168:171], v[208:211], v[0:3]
	v_mfma_f32_16x16x32_bf16 v[52:55], v[164:167], v[188:191], v[52:55]
	v_mfma_f32_16x16x32_bf16 v[48:51], v[172:175], v[188:191], v[48:51]
	v_mfma_f32_16x16x32_bf16 v[36:39], v[164:167], v[196:199], v[36:39]
	v_mfma_f32_16x16x32_bf16 v[32:35], v[172:175], v[196:199], v[32:35]
	s_setprio 2
	s_barrier
	v_mfma_f32_16x16x32_bf16 v[20:23], v[164:167], v[204:207], v[20:23]
	v_mfma_f32_16x16x32_bf16 v[16:19], v[172:175], v[204:207], v[16:19]
	v_mfma_f32_16x16x32_bf16 v[4:7], v[164:167], v[212:215], v[4:7]
	v_mfma_f32_16x16x32_bf16 v[0:3], v[172:175], v[212:215], v[0:3]
	s_setprio 0
	s_add_i32 s73, s73, 2
	s_add_u32 s6, s6, 0x100
	s_addc_u32 s7, s7, 0
	s_add_u32 s71, s71, 0x100
	s_addc_u32 s72, s72, 0
	s_cmp_gt_u32 s73, 13
	s_cbranch_scc0 .LBB0_952
	s_and_b64 vcc, exec, s[24:25]
	s_cbranch_vccz .LBB0_955
	s_barrier

.LBB0_1146:
	ds_read_b128 v[120:123], v233
	ds_read_b128 v[132:135], v233 offset:1024
	ds_read_b128 v[136:139], v233 offset:2048
	ds_read_b128 v[140:143], v233 offset:3072
	ds_read_b128 v[144:147], v234
	ds_read_b128 v[148:151], v234 offset:1024
	ds_read_b128 v[152:155], v234 offset:2048
	ds_read_b128 v[156:159], v234 offset:3072
	s_add_u32 s40, s38, 0xfffc0080
	s_addc_u32 s41, s39, -1
	s_cmp_eq_u32 s66, 12
	s_cselect_b32 s43, s23, s41
	s_cselect_b32 s42, s31, s40
	s_cselect_b32 s41, s25, s65
	s_cselect_b32 s40, s37, s64
	v_lshl_add_u64 v[208:209], s[38:39], 0, v[192:193]
	s_add_i32 m0, s50, 0xc000
	ds_read_b128 v[160:163], v235
	ds_read_b128 v[164:167], v235 offset:1024
	ds_read_b128 v[168:171], v235 offset:2048
	ds_read_b128 v[172:175], v235 offset:3072
	ds_read_b128 v[176:179], v235 offset:4096
	ds_read_b128 v[180:183], v235 offset:5120
	ds_read_b128 v[200:203], v235 offset:6144
	ds_read_b128 v[204:207], v235 offset:7168
	global_load_lds_dwordx4 v[208:209], off
	v_lshl_add_u64 v[208:209], s[38:39], 0, v[194:195]
	s_add_i32 m0, s50, 0xe000
	s_nop 0
	global_load_lds_dwordx4 v[208:209], off
	s_waitcnt vmcnt(8)
	s_waitcnt lgkmcnt(0)
	s_barrier
	s_setprio 1
	s_waitcnt lgkmcnt(0)
	v_mfma_f32_16x16x32_bf16 v[128:131], v[120:123], v[160:163], v[128:131]
	v_mfma_f32_16x16x32_bf16 v[124:127], v[136:139], v[160:163], v[124:127]
	v_mfma_f32_16x16x32_bf16 v[108:111], v[120:123], v[168:171], v[108:111]
	v_mfma_f32_16x16x32_bf16 v[104:107], v[136:139], v[168:171], v[104:107]
	v_mfma_f32_16x16x32_bf16 v[92:95], v[120:123], v[176:179], v[92:95]
	v_mfma_f32_16x16x32_bf16 v[88:91], v[136:139], v[176:179], v[88:91]
	v_mfma_f32_16x16x32_bf16 v[76:79], v[120:123], v[200:203], v[76:79]
	v_mfma_f32_16x16x32_bf16 v[72:75], v[136:139], v[200:203], v[72:75]
	v_mfma_f32_16x16x32_bf16 v[128:131], v[132:135], v[164:167], v[128:131]
	v_mfma_f32_16x16x32_bf16 v[124:127], v[140:143], v[164:167], v[124:127]
	v_mfma_f32_16x16x32_bf16 v[108:111], v[132:135], v[172:175], v[108:111]
	v_mfma_f32_16x16x32_bf16 v[104:107], v[140:143], v[172:175], v[104:107]
	v_mfma_f32_16x16x32_bf16 v[92:95], v[132:135], v[180:183], v[92:95]
	v_mfma_f32_16x16x32_bf16 v[88:91], v[140:143], v[180:183], v[88:91]
	v_mfma_f32_16x16x32_bf16 v[76:79], v[132:135], v[204:207], v[76:79]
	v_mfma_f32_16x16x32_bf16 v[72:75], v[140:143], v[204:207], v[72:75]
	s_setprio 0
	s_setprio 1
	v_mfma_f32_16x16x32_bf16 v[116:119], v[144:147], v[160:163], v[116:119]
	v_mfma_f32_16x16x32_bf16 v[112:115], v[152:155], v[160:163], v[112:115]
	v_mfma_f32_16x16x32_bf16 v[100:103], v[144:147], v[168:171], v[100:103]
	v_mfma_f32_16x16x32_bf16 v[96:99], v[152:155], v[168:171], v[96:99]
	v_mfma_f32_16x16x32_bf16 v[84:87], v[144:147], v[176:179], v[84:87]
	v_mfma_f32_16x16x32_bf16 v[80:83], v[152:155], v[176:179], v[80:83]
	v_mfma_f32_16x16x32_bf16 v[68:71], v[144:147], v[200:203], v[68:71]
	v_mfma_f32_16x16x32_bf16 v[64:67], v[152:155], v[200:203], v[64:67]
	v_mfma_f32_16x16x32_bf16 v[116:119], v[148:151], v[164:167], v[116:119]
	v_mfma_f32_16x16x32_bf16 v[112:115], v[156:159], v[164:167], v[112:115]
	v_mfma_f32_16x16x32_bf16 v[100:103], v[148:151], v[172:175], v[100:103]
	v_mfma_f32_16x16x32_bf16 v[96:99], v[156:159], v[172:175], v[96:99]
	s_setprio 2
	s_barrier
	v_mfma_f32_16x16x32_bf16 v[84:87], v[148:151], v[180:183], v[84:87]
	v_mfma_f32_16x16x32_bf16 v[80:83], v[156:159], v[180:183], v[80:83]
	v_mfma_f32_16x16x32_bf16 v[68:71], v[148:151], v[204:207], v[68:71]
	v_mfma_f32_16x16x32_bf16 v[64:67], v[156:159], v[204:207], v[64:67]
	s_setprio 0
	s_add_i32 s67, s62, s49
	v_lshl_add_u64 v[208:209], s[40:41], 0, v[186:187]
	s_mov_b32 m0, s67
	ds_read_b128 v[160:163], v235 offset:16384
	ds_read_b128 v[164:167], v235 offset:17408
	ds_read_b128 v[168:171], v235 offset:18432
	ds_read_b128 v[172:175], v235 offset:19456
	ds_read_b128 v[176:179], v235 offset:20480
	ds_read_b128 v[180:183], v235 offset:21504
	ds_read_b128 v[200:203], v235 offset:22528
	ds_read_b128 v[204:207], v235 offset:23552
	global_load_lds_dwordx4 v[208:209], off
	s_add_i32 m0, s67, 0x2000
	s_add_u32 s68, s40, 0x40000
	v_lshl_add_u64 v[210:211], s[40:41], 0, v[190:191]
	s_addc_u32 s69, s41, 0
	s_add_i32 s67, s63, s49
	global_load_lds_dwordx4 v[210:211], off
	v_lshl_add_u64 v[212:213], s[68:69], 0, v[186:187]
	s_mov_b32 m0, s67
	v_lshl_add_u64 v[214:215], s[42:43], 0, v[188:189]
	global_load_lds_dwordx4 v[212:213], off
	v_lshl_add_u64 v[212:213], s[68:69], 0, v[190:191]
	s_add_i32 m0, s67, 0x2000
	s_nop 0
	global_load_lds_dwordx4 v[212:213], off
	v_lshl_add_u64 v[212:213], s[42:43], 0, v[184:185]
	s_mov_b32 m0, s50
	s_nop 0
	global_load_lds_dwordx4 v[212:213], off
	s_mov_b32 m0, s51
	s_nop 0
	global_load_lds_dwordx4 v[214:215], off
	s_waitcnt vmcnt(8)
	s_waitcnt lgkmcnt(0)
	s_barrier
	s_setprio 1
	s_waitcnt lgkmcnt(0)
	v_mfma_f32_16x16x32_bf16 v[60:63], v[120:123], v[160:163], v[60:63]
	v_mfma_f32_16x16x32_bf16 v[56:59], v[136:139], v[160:163], v[56:59]
	v_mfma_f32_16x16x32_bf16 v[44:47], v[120:123], v[168:171], v[44:47]
	v_mfma_f32_16x16x32_bf16 v[40:43], v[136:139], v[168:171], v[40:43]
	v_mfma_f32_16x16x32_bf16 v[28:31], v[120:123], v[176:179], v[28:31]
	v_mfma_f32_16x16x32_bf16 v[24:27], v[136:139], v[176:179], v[24:27]
	v_mfma_f32_16x16x32_bf16 v[12:15], v[120:123], v[200:203], v[12:15]
	v_mfma_f32_16x16x32_bf16 v[8:11], v[136:139], v[200:203], v[8:11]
	v_mfma_f32_16x16x32_bf16 v[60:63], v[132:135], v[164:167], v[60:63]
	v_mfma_f32_16x16x32_bf16 v[56:59], v[140:143], v[164:167], v[56:59]
	v_mfma_f32_16x16x32_bf16 v[44:47], v[132:135], v[172:175], v[44:47]
	v_mfma_f32_16x16x32_bf16 v[40:43], v[140:143], v[172:175], v[40:43]
	v_mfma_f32_16x16x32_bf16 v[28:31], v[132:135], v[180:183], v[28:31]
	v_mfma_f32_16x16x32_bf16 v[24:27], v[140:143], v[180:183], v[24:27]
	v_mfma_f32_16x16x32_bf16 v[12:15], v[132:135], v[204:207], v[12:15]
	v_mfma_f32_16x16x32_bf16 v[8:11], v[140:143], v[204:207], v[8:11]
	s_setprio 0
	s_setprio 1
	v_mfma_f32_16x16x32_bf16 v[52:55], v[144:147], v[160:163], v[52:55]
	v_mfma_f32_16x16x32_bf16 v[48:51], v[152:155], v[160:163], v[48:51]
	v_mfma_f32_16x16x32_bf16 v[36:39], v[144:147], v[168:171], v[36:39]
	v_mfma_f32_16x16x32_bf16 v[32:35], v[152:155], v[168:171], v[32:35]
	v_mfma_f32_16x16x32_bf16 v[20:23], v[144:147], v[176:179], v[20:23]
	v_mfma_f32_16x16x32_bf16 v[16:19], v[152:155], v[176:179], v[16:19]
	v_mfma_f32_16x16x32_bf16 v[4:7], v[144:147], v[200:203], v[4:7]
	v_mfma_f32_16x16x32_bf16 v[0:3], v[152:155], v[200:203], v[0:3]
	v_mfma_f32_16x16x32_bf16 v[52:55], v[148:151], v[164:167], v[52:55]
	v_mfma_f32_16x16x32_bf16 v[48:51], v[156:159], v[164:167], v[48:51]
	v_mfma_f32_16x16x32_bf16 v[36:39], v[148:151], v[172:175], v[36:39]
	v_mfma_f32_16x16x32_bf16 v[32:35], v[156:159], v[172:175], v[32:35]
	s_setprio 2
	s_barrier
	v_mfma_f32_16x16x32_bf16 v[20:23], v[148:151], v[180:183], v[20:23]
	v_mfma_f32_16x16x32_bf16 v[16:19], v[156:159], v[180:183], v[16:19]
	v_mfma_f32_16x16x32_bf16 v[4:7], v[148:151], v[204:207], v[4:7]
	v_mfma_f32_16x16x32_bf16 v[0:3], v[156:159], v[204:207], v[0:3]
	s_setprio 0
	s_add_i32 s67, 0, 0x18000
	s_add_i32 s68, 0, 0x1c000
	v_add_u32_e32 v140, s67, v232
	v_add_u32_e32 v156, s68, v232
	ds_read_b128 v[120:123], v140
	ds_read_b128 v[132:135], v140 offset:1024
	ds_read_b128 v[136:139], v140 offset:2048
	ds_read_b128 v[140:143], v140 offset:3072
	ds_read_b128 v[144:147], v156
	ds_read_b128 v[148:151], v156 offset:1024
	ds_read_b128 v[152:155], v156 offset:2048
	ds_read_b128 v[156:159], v156 offset:3072
	s_add_u32 s42, s42, 0x40000
	s_addc_u32 s43, s43, 0
	s_mov_b32 m0, s54
	v_lshl_add_u64 v[216:217], s[42:43], 0, v[184:185]
	ds_read_b128 v[160:163], v235 offset:32768
	ds_read_b128 v[164:167], v235 offset:33792
	ds_read_b128 v[168:171], v235 offset:34816
	ds_read_b128 v[172:175], v235 offset:35840
	ds_read_b128 v[176:179], v235 offset:36864
	ds_read_b128 v[180:183], v235 offset:37888
	ds_read_b128 v[200:203], v235 offset:38912
	ds_read_b128 v[204:207], v235 offset:39936
	global_load_lds_dwordx4 v[216:217], off
	v_lshl_add_u64 v[216:217], s[42:43], 0, v[188:189]
	s_mov_b32 m0, s55
	s_nop 0
	global_load_lds_dwordx4 v[216:217], off
	s_waitcnt vmcnt(8)
	s_waitcnt lgkmcnt(0)
	s_barrier
	s_setprio 1
	s_waitcnt lgkmcnt(0)
	v_mfma_f32_16x16x32_bf16 v[128:131], v[120:123], v[160:163], v[128:131]
	v_mfma_f32_16x16x32_bf16 v[124:127], v[136:139], v[160:163], v[124:127]
	v_mfma_f32_16x16x32_bf16 v[108:111], v[120:123], v[168:171], v[108:111]
	v_mfma_f32_16x16x32_bf16 v[104:107], v[136:139], v[168:171], v[104:107]
	v_mfma_f32_16x16x32_bf16 v[92:95], v[120:123], v[176:179], v[92:95]
	v_mfma_f32_16x16x32_bf16 v[88:91], v[136:139], v[176:179], v[88:91]
	v_mfma_f32_16x16x32_bf16 v[76:79], v[120:123], v[200:203], v[76:79]
	v_mfma_f32_16x16x32_bf16 v[72:75], v[136:139], v[200:203], v[72:75]
	v_mfma_f32_16x16x32_bf16 v[128:131], v[132:135], v[164:167], v[128:131]
	v_mfma_f32_16x16x32_bf16 v[124:127], v[140:143], v[164:167], v[124:127]
	v_mfma_f32_16x16x32_bf16 v[108:111], v[132:135], v[172:175], v[108:111]
	v_mfma_f32_16x16x32_bf16 v[104:107], v[140:143], v[172:175], v[104:107]
	v_mfma_f32_16x16x32_bf16 v[92:95], v[132:135], v[180:183], v[92:95]
	v_mfma_f32_16x16x32_bf16 v[88:91], v[140:143], v[180:183], v[88:91]
	v_mfma_f32_16x16x32_bf16 v[76:79], v[132:135], v[204:207], v[76:79]
	v_mfma_f32_16x16x32_bf16 v[72:75], v[140:143], v[204:207], v[72:75]
	s_setprio 0
	s_setprio 1
	v_mfma_f32_16x16x32_bf16 v[116:119], v[144:147], v[160:163], v[116:119]
	v_mfma_f32_16x16x32_bf16 v[112:115], v[152:155], v[160:163], v[112:115]
	v_mfma_f32_16x16x32_bf16 v[100:103], v[144:147], v[168:171], v[100:103]
	v_mfma_f32_16x16x32_bf16 v[96:99], v[152:155], v[168:171], v[96:99]
	v_mfma_f32_16x16x32_bf16 v[84:87], v[144:147], v[176:179], v[84:87]
	v_mfma_f32_16x16x32_bf16 v[80:83], v[152:155], v[176:179], v[80:83]
	v_mfma_f32_16x16x32_bf16 v[68:71], v[144:147], v[200:203], v[68:71]
	v_mfma_f32_16x16x32_bf16 v[64:67], v[152:155], v[200:203], v[64:67]
	v_mfma_f32_16x16x32_bf16 v[116:119], v[148:151], v[164:167], v[116:119]
	v_mfma_f32_16x16x32_bf16 v[112:115], v[156:159], v[164:167], v[112:115]
	v_mfma_f32_16x16x32_bf16 v[100:103], v[148:151], v[172:175], v[100:103]
	v_mfma_f32_16x16x32_bf16 v[96:99], v[156:159], v[172:175], v[96:99]
	s_setprio 2
	s_barrier
	v_mfma_f32_16x16x32_bf16 v[84:87], v[148:151], v[180:183], v[84:87]
	v_mfma_f32_16x16x32_bf16 v[80:83], v[156:159], v[180:183], v[80:83]
	v_mfma_f32_16x16x32_bf16 v[68:71], v[148:151], v[204:207], v[68:71]
	v_mfma_f32_16x16x32_bf16 v[64:67], v[156:159], v[204:207], v[64:67]
	s_setprio 0
	s_add_i32 s42, s67, s49
	v_lshl_add_u64 v[208:209], v[208:209], 0, s[18:19]
	s_mov_b32 m0, s42
	ds_read_b128 v[160:163], v235 offset:49152
	ds_read_b128 v[164:167], v235 offset:50176
	ds_read_b128 v[168:171], v235 offset:51200
	ds_read_b128 v[172:175], v235 offset:52224
	ds_read_b128 v[176:179], v235 offset:53248
	ds_read_b128 v[180:183], v235 offset:54272
	ds_read_b128 v[200:203], v235 offset:55296
	ds_read_b128 v[204:207], v235 offset:56320
	global_load_lds_dwordx4 v[208:209], off
	s_add_i32 m0, s42, 0x2000
	s_add_u32 s40, s40, 0x40080
	v_lshl_add_u64 v[208:209], v[210:211], 0, s[18:19]
	s_addc_u32 s41, s41, 0
	s_add_i32 s42, s68, s49
	global_load_lds_dwordx4 v[208:209], off
	v_lshl_add_u64 v[208:209], s[40:41], 0, v[186:187]
	s_mov_b32 m0, s42
	s_nop 0
	global_load_lds_dwordx4 v[208:209], off
	v_lshl_add_u64 v[208:209], s[40:41], 0, v[190:191]
	s_add_i32 m0, s42, 0x2000
	s_nop 0
	global_load_lds_dwordx4 v[208:209], off
	v_lshl_add_u64 v[208:209], v[212:213], 0, s[18:19]
	s_mov_b32 m0, s57
	s_nop 0
	global_load_lds_dwordx4 v[208:209], off
	v_lshl_add_u64 v[208:209], v[214:215], 0, s[18:19]
	s_mov_b32 m0, s58
	s_nop 0
	global_load_lds_dwordx4 v[208:209], off
	s_waitcnt vmcnt(8)
	s_waitcnt lgkmcnt(0)
	s_barrier
	s_setprio 1
	s_waitcnt lgkmcnt(0)
	v_mfma_f32_16x16x32_bf16 v[60:63], v[120:123], v[160:163], v[60:63]
	v_mfma_f32_16x16x32_bf16 v[56:59], v[136:139], v[160:163], v[56:59]
	v_mfma_f32_16x16x32_bf16 v[44:47], v[120:123], v[168:171], v[44:47]
	v_mfma_f32_16x16x32_bf16 v[40:43], v[136:139], v[168:171], v[40:43]
	v_mfma_f32_16x16x32_bf16 v[28:31], v[120:123], v[176:179], v[28:31]
	v_mfma_f32_16x16x32_bf16 v[24:27], v[136:139], v[176:179], v[24:27]
	v_mfma_f32_16x16x32_bf16 v[12:15], v[120:123], v[200:203], v[12:15]
	v_mfma_f32_16x16x32_bf16 v[8:11], v[136:139], v[200:203], v[8:11]
	v_mfma_f32_16x16x32_bf16 v[60:63], v[132:135], v[164:167], v[60:63]
	v_mfma_f32_16x16x32_bf16 v[56:59], v[140:143], v[164:167], v[56:59]
	v_mfma_f32_16x16x32_bf16 v[44:47], v[132:135], v[172:175], v[44:47]
	v_mfma_f32_16x16x32_bf16 v[40:43], v[140:143], v[172:175], v[40:43]
	v_mfma_f32_16x16x32_bf16 v[28:31], v[132:135], v[180:183], v[28:31]
	v_mfma_f32_16x16x32_bf16 v[24:27], v[140:143], v[180:183], v[24:27]
	v_mfma_f32_16x16x32_bf16 v[12:15], v[132:135], v[204:207], v[12:15]
	v_mfma_f32_16x16x32_bf16 v[8:11], v[140:143], v[204:207], v[8:11]
	s_setprio 0
	s_setprio 1
	v_mfma_f32_16x16x32_bf16 v[52:55], v[144:147], v[160:163], v[52:55]
	v_mfma_f32_16x16x32_bf16 v[48:51], v[152:155], v[160:163], v[48:51]
	v_mfma_f32_16x16x32_bf16 v[36:39], v[144:147], v[168:171], v[36:39]
	v_mfma_f32_16x16x32_bf16 v[32:35], v[152:155], v[168:171], v[32:35]
	v_mfma_f32_16x16x32_bf16 v[20:23], v[144:147], v[176:179], v[20:23]
	v_mfma_f32_16x16x32_bf16 v[16:19], v[152:155], v[176:179], v[16:19]
	v_mfma_f32_16x16x32_bf16 v[4:7], v[144:147], v[200:203], v[4:7]
	v_mfma_f32_16x16x32_bf16 v[0:3], v[152:155], v[200:203], v[0:3]
	v_mfma_f32_16x16x32_bf16 v[52:55], v[148:151], v[164:167], v[52:55]
	v_mfma_f32_16x16x32_bf16 v[48:51], v[156:159], v[164:167], v[48:51]
	v_mfma_f32_16x16x32_bf16 v[36:39], v[148:151], v[172:175], v[36:39]
	v_mfma_f32_16x16x32_bf16 v[32:35], v[156:159], v[172:175], v[32:35]
	s_setprio 2
	s_barrier
	v_mfma_f32_16x16x32_bf16 v[20:23], v[148:151], v[180:183], v[20:23]
	v_mfma_f32_16x16x32_bf16 v[16:19], v[156:159], v[180:183], v[16:19]
	v_mfma_f32_16x16x32_bf16 v[4:7], v[148:151], v[204:207], v[4:7]
	v_mfma_f32_16x16x32_bf16 v[0:3], v[156:159], v[204:207], v[0:3]
	s_setprio 0
	s_add_i32 s66, s66, 2
	s_add_u32 s38, s38, 0x100
	s_addc_u32 s39, s39, 0
	s_add_u32 s64, s64, 0x100
	s_addc_u32 s65, s65, 0
	s_cmp_gt_u32 s66, 13
	s_cbranch_scc0 .LBB0_1146
	s_and_b64 vcc, exec, s[20:21]
	s_cbranch_vccz .LBB0_1149
	s_barrier

.LBB0_1310:
	ds_read_b128 v[128:131], v197
	ds_read_b128 v[132:135], v197 offset:1024
	ds_read_b128 v[136:139], v197 offset:2048
	ds_read_b128 v[140:143], v197 offset:3072
	ds_read_b128 v[144:147], v198
	ds_read_b128 v[148:151], v198 offset:1024
	ds_read_b128 v[152:155], v198 offset:2048
	ds_read_b128 v[156:159], v198 offset:3072
	s_add_u32 s4, s24, 0x100
	s_addc_u32 s5, s25, 0
	s_cmp_eq_u32 s53, 40
	s_cselect_b32 s29, s21, s5
	s_cselect_b32 s28, s20, s4
	s_cselect_b32 s27, s23, s52
	s_cselect_b32 s26, s22, s51
	v_lshl_add_u64 v[212:213], s[24:25], 0, v[172:173]
	s_add_i32 m0, s36, 0xc000
	ds_read_b128 v[160:163], v199
	ds_read_b128 v[180:183], v199 offset:1024
	ds_read_b128 v[184:187], v199 offset:2048
	ds_read_b128 v[188:191], v199 offset:3072
	ds_read_b128 v[192:195], v199 offset:4096
	ds_read_b128 v[200:203], v199 offset:5120
	ds_read_b128 v[204:207], v199 offset:6144
	ds_read_b128 v[208:211], v199 offset:7168
	global_load_lds_dwordx4 v[212:213], off
	v_lshl_add_u64 v[212:213], s[24:25], 0, v[174:175]
	s_add_i32 m0, s36, 0xe000
	s_nop 0
	global_load_lds_dwordx4 v[212:213], off
	s_waitcnt vmcnt(8)
	s_waitcnt lgkmcnt(0)
	s_barrier
	s_setprio 1
	s_waitcnt lgkmcnt(0)
	v_mfma_f32_16x16x32_bf16 v[124:127], v[128:131], v[160:163], v[124:127]
	v_mfma_f32_16x16x32_bf16 v[120:123], v[136:139], v[160:163], v[120:123]
	v_mfma_f32_16x16x32_bf16 v[116:119], v[128:131], v[184:187], v[116:119]
	v_mfma_f32_16x16x32_bf16 v[108:111], v[136:139], v[184:187], v[108:111]
	v_mfma_f32_16x16x32_bf16 v[88:91], v[128:131], v[192:195], v[88:91]
	v_mfma_f32_16x16x32_bf16 v[100:103], v[136:139], v[192:195], v[100:103]
	v_mfma_f32_16x16x32_bf16 v[72:75], v[128:131], v[204:207], v[72:75]
	v_mfma_f32_16x16x32_bf16 v[76:79], v[136:139], v[204:207], v[76:79]
	v_mfma_f32_16x16x32_bf16 v[124:127], v[132:135], v[180:183], v[124:127]
	v_mfma_f32_16x16x32_bf16 v[120:123], v[140:143], v[180:183], v[120:123]
	v_mfma_f32_16x16x32_bf16 v[116:119], v[132:135], v[188:191], v[116:119]
	v_mfma_f32_16x16x32_bf16 v[108:111], v[140:143], v[188:191], v[108:111]
	v_mfma_f32_16x16x32_bf16 v[88:91], v[132:135], v[200:203], v[88:91]
	v_mfma_f32_16x16x32_bf16 v[100:103], v[140:143], v[200:203], v[100:103]
	v_mfma_f32_16x16x32_bf16 v[72:75], v[132:135], v[208:211], v[72:75]
	v_mfma_f32_16x16x32_bf16 v[76:79], v[140:143], v[208:211], v[76:79]
	s_setprio 0
	s_setprio 1
	v_mfma_f32_16x16x32_bf16 v[112:115], v[144:147], v[160:163], v[112:115]
	v_mfma_f32_16x16x32_bf16 v[104:107], v[152:155], v[160:163], v[104:107]
	v_mfma_f32_16x16x32_bf16 v[96:99], v[144:147], v[184:187], v[96:99]
	v_mfma_f32_16x16x32_bf16 v[92:95], v[152:155], v[184:187], v[92:95]
	v_mfma_f32_16x16x32_bf16 v[80:83], v[144:147], v[192:195], v[80:83]
	v_mfma_f32_16x16x32_bf16 v[84:87], v[152:155], v[192:195], v[84:87]
	v_mfma_f32_16x16x32_bf16 v[64:67], v[144:147], v[204:207], v[64:67]
	v_mfma_f32_16x16x32_bf16 v[68:71], v[152:155], v[204:207], v[68:71]
	v_mfma_f32_16x16x32_bf16 v[112:115], v[148:151], v[180:183], v[112:115]
	v_mfma_f32_16x16x32_bf16 v[104:107], v[156:159], v[180:183], v[104:107]
	v_mfma_f32_16x16x32_bf16 v[96:99], v[148:151], v[188:191], v[96:99]
	v_mfma_f32_16x16x32_bf16 v[92:95], v[156:159], v[188:191], v[92:95]
	s_setprio 2
	s_barrier
	v_mfma_f32_16x16x32_bf16 v[80:83], v[148:151], v[200:203], v[80:83]
	v_mfma_f32_16x16x32_bf16 v[84:87], v[156:159], v[200:203], v[84:87]
	v_mfma_f32_16x16x32_bf16 v[64:67], v[148:151], v[208:211], v[64:67]
	v_mfma_f32_16x16x32_bf16 v[68:71], v[156:159], v[208:211], v[68:71]
	s_setprio 0
	s_add_i32 s24, s45, s35
	v_lshl_add_u64 v[212:213], s[26:27], 0, v[166:167]
	s_mov_b32 m0, s24
	ds_read_b128 v[160:163], v199 offset:16384
	ds_read_b128 v[180:183], v199 offset:17408
	ds_read_b128 v[184:187], v199 offset:18432
	ds_read_b128 v[188:191], v199 offset:19456
	ds_read_b128 v[192:195], v199 offset:20480
	ds_read_b128 v[200:203], v199 offset:21504
	ds_read_b128 v[204:207], v199 offset:22528
	ds_read_b128 v[208:211], v199 offset:23552
	global_load_lds_dwordx4 v[212:213], off
	s_add_i32 m0, s24, 0x2000
	s_add_u32 s24, s26, 0xb0000
	v_lshl_add_u64 v[214:215], s[26:27], 0, v[170:171]
	s_addc_u32 s25, s27, 0
	s_add_i32 s54, s46, s35
	global_load_lds_dwordx4 v[214:215], off
	v_lshl_add_u64 v[216:217], s[24:25], 0, v[166:167]
	s_mov_b32 m0, s54
	v_lshl_add_u64 v[218:219], s[28:29], 0, v[168:169]
	global_load_lds_dwordx4 v[216:217], off
	v_lshl_add_u64 v[216:217], s[24:25], 0, v[170:171]
	s_add_i32 m0, s54, 0x2000
	s_nop 0
	global_load_lds_dwordx4 v[216:217], off
	v_lshl_add_u64 v[216:217], s[28:29], 0, v[164:165]
	s_mov_b32 m0, s36
	s_nop 0
	global_load_lds_dwordx4 v[216:217], off
	s_mov_b32 m0, s37
	s_nop 0
	global_load_lds_dwordx4 v[218:219], off
	s_waitcnt vmcnt(8)
	s_waitcnt lgkmcnt(0)
	s_barrier
	s_setprio 1
	s_waitcnt lgkmcnt(0)
	v_mfma_f32_16x16x32_bf16 v[56:59], v[128:131], v[160:163], v[56:59]
	v_mfma_f32_16x16x32_bf16 v[60:63], v[136:139], v[160:163], v[60:63]
	v_mfma_f32_16x16x32_bf16 v[40:43], v[128:131], v[184:187], v[40:43]
	v_mfma_f32_16x16x32_bf16 v[44:47], v[136:139], v[184:187], v[44:47]
	v_mfma_f32_16x16x32_bf16 v[24:27], v[128:131], v[192:195], v[24:27]
	v_mfma_f32_16x16x32_bf16 v[28:31], v[136:139], v[192:195], v[28:31]
	v_mfma_f32_16x16x32_bf16 v[8:11], v[128:131], v[204:207], v[8:11]
	v_mfma_f32_16x16x32_bf16 v[12:15], v[136:139], v[204:207], v[12:15]
	v_mfma_f32_16x16x32_bf16 v[56:59], v[132:135], v[180:183], v[56:59]
	v_mfma_f32_16x16x32_bf16 v[60:63], v[140:143], v[180:183], v[60:63]
	v_mfma_f32_16x16x32_bf16 v[40:43], v[132:135], v[188:191], v[40:43]
	v_mfma_f32_16x16x32_bf16 v[44:47], v[140:143], v[188:191], v[44:47]
	v_mfma_f32_16x16x32_bf16 v[24:27], v[132:135], v[200:203], v[24:27]
	v_mfma_f32_16x16x32_bf16 v[28:31], v[140:143], v[200:203], v[28:31]
	v_mfma_f32_16x16x32_bf16 v[8:11], v[132:135], v[208:211], v[8:11]
	v_mfma_f32_16x16x32_bf16 v[12:15], v[140:143], v[208:211], v[12:15]
	s_setprio 0
	s_setprio 1
	v_mfma_f32_16x16x32_bf16 v[48:51], v[144:147], v[160:163], v[48:51]
	v_mfma_f32_16x16x32_bf16 v[52:55], v[152:155], v[160:163], v[52:55]
	v_mfma_f32_16x16x32_bf16 v[32:35], v[144:147], v[184:187], v[32:35]
	v_mfma_f32_16x16x32_bf16 v[36:39], v[152:155], v[184:187], v[36:39]
	v_mfma_f32_16x16x32_bf16 v[16:19], v[144:147], v[192:195], v[16:19]
	v_mfma_f32_16x16x32_bf16 v[20:23], v[152:155], v[192:195], v[20:23]
	v_mfma_f32_16x16x32_bf16 v[0:3], v[144:147], v[204:207], v[0:3]
	v_mfma_f32_16x16x32_bf16 v[4:7], v[152:155], v[204:207], v[4:7]
	v_mfma_f32_16x16x32_bf16 v[48:51], v[148:151], v[180:183], v[48:51]
	v_mfma_f32_16x16x32_bf16 v[52:55], v[156:159], v[180:183], v[52:55]
	v_mfma_f32_16x16x32_bf16 v[32:35], v[148:151], v[188:191], v[32:35]
	v_mfma_f32_16x16x32_bf16 v[36:39], v[156:159], v[188:191], v[36:39]
	s_setprio 2
	s_barrier
	v_mfma_f32_16x16x32_bf16 v[16:19], v[148:151], v[200:203], v[16:19]
	v_mfma_f32_16x16x32_bf16 v[20:23], v[156:159], v[200:203], v[20:23]
	v_mfma_f32_16x16x32_bf16 v[0:3], v[148:151], v[208:211], v[0:3]
	v_mfma_f32_16x16x32_bf16 v[4:7], v[156:159], v[208:211], v[4:7]
	s_setprio 0
	s_add_i32 s54, 0, 0x18000
	s_add_i32 s55, 0, 0x1c000
	v_add_u32_e32 v140, s54, v196
	v_add_u32_e32 v156, s55, v196
	ds_read_b128 v[128:131], v140
	ds_read_b128 v[132:135], v140 offset:1024
	ds_read_b128 v[136:139], v140 offset:2048
	ds_read_b128 v[140:143], v140 offset:3072
	ds_read_b128 v[144:147], v156
	ds_read_b128 v[148:151], v156 offset:1024
	ds_read_b128 v[152:155], v156 offset:2048
	ds_read_b128 v[156:159], v156 offset:3072
	s_add_u32 s24, s28, 0xb0000
	s_addc_u32 s25, s29, 0
	s_mov_b32 m0, s38
	v_lshl_add_u64 v[220:221], s[24:25], 0, v[164:165]
	ds_read_b128 v[160:163], v199 offset:32768
	ds_read_b128 v[180:183], v199 offset:33792
	ds_read_b128 v[184:187], v199 offset:34816
	ds_read_b128 v[188:191], v199 offset:35840
	ds_read_b128 v[192:195], v199 offset:36864
	ds_read_b128 v[200:203], v199 offset:37888
	ds_read_b128 v[204:207], v199 offset:38912
	ds_read_b128 v[208:211], v199 offset:39936
	global_load_lds_dwordx4 v[220:221], off
	v_lshl_add_u64 v[220:221], s[24:25], 0, v[168:169]
	s_mov_b32 m0, s39
	s_nop 0
	global_load_lds_dwordx4 v[220:221], off
	s_waitcnt vmcnt(8)
	s_waitcnt lgkmcnt(0)
	s_barrier
	s_setprio 1
	s_waitcnt lgkmcnt(0)
	v_mfma_f32_16x16x32_bf16 v[124:127], v[128:131], v[160:163], v[124:127]
	v_mfma_f32_16x16x32_bf16 v[120:123], v[136:139], v[160:163], v[120:123]
	v_mfma_f32_16x16x32_bf16 v[116:119], v[128:131], v[184:187], v[116:119]
	v_mfma_f32_16x16x32_bf16 v[108:111], v[136:139], v[184:187], v[108:111]
	v_mfma_f32_16x16x32_bf16 v[88:91], v[128:131], v[192:195], v[88:91]
	v_mfma_f32_16x16x32_bf16 v[100:103], v[136:139], v[192:195], v[100:103]
	v_mfma_f32_16x16x32_bf16 v[72:75], v[128:131], v[204:207], v[72:75]
	v_mfma_f32_16x16x32_bf16 v[76:79], v[136:139], v[204:207], v[76:79]
	v_mfma_f32_16x16x32_bf16 v[124:127], v[132:135], v[180:183], v[124:127]
	v_mfma_f32_16x16x32_bf16 v[120:123], v[140:143], v[180:183], v[120:123]
	v_mfma_f32_16x16x32_bf16 v[116:119], v[132:135], v[188:191], v[116:119]
	v_mfma_f32_16x16x32_bf16 v[108:111], v[140:143], v[188:191], v[108:111]
	v_mfma_f32_16x16x32_bf16 v[88:91], v[132:135], v[200:203], v[88:91]
	v_mfma_f32_16x16x32_bf16 v[100:103], v[140:143], v[200:203], v[100:103]
	v_mfma_f32_16x16x32_bf16 v[72:75], v[132:135], v[208:211], v[72:75]
	v_mfma_f32_16x16x32_bf16 v[76:79], v[140:143], v[208:211], v[76:79]
	s_setprio 0
	s_setprio 1
	v_mfma_f32_16x16x32_bf16 v[112:115], v[144:147], v[160:163], v[112:115]
	v_mfma_f32_16x16x32_bf16 v[104:107], v[152:155], v[160:163], v[104:107]
	v_mfma_f32_16x16x32_bf16 v[96:99], v[144:147], v[184:187], v[96:99]
	v_mfma_f32_16x16x32_bf16 v[92:95], v[152:155], v[184:187], v[92:95]
	v_mfma_f32_16x16x32_bf16 v[80:83], v[144:147], v[192:195], v[80:83]
	v_mfma_f32_16x16x32_bf16 v[84:87], v[152:155], v[192:195], v[84:87]
	v_mfma_f32_16x16x32_bf16 v[64:67], v[144:147], v[204:207], v[64:67]
	v_mfma_f32_16x16x32_bf16 v[68:71], v[152:155], v[204:207], v[68:71]
	v_mfma_f32_16x16x32_bf16 v[112:115], v[148:151], v[180:183], v[112:115]
	v_mfma_f32_16x16x32_bf16 v[104:107], v[156:159], v[180:183], v[104:107]
	v_mfma_f32_16x16x32_bf16 v[96:99], v[148:151], v[188:191], v[96:99]
	v_mfma_f32_16x16x32_bf16 v[92:95], v[156:159], v[188:191], v[92:95]
	s_setprio 2
	s_barrier
	v_mfma_f32_16x16x32_bf16 v[80:83], v[148:151], v[200:203], v[80:83]
	v_mfma_f32_16x16x32_bf16 v[84:87], v[156:159], v[200:203], v[84:87]
	v_mfma_f32_16x16x32_bf16 v[64:67], v[148:151], v[208:211], v[64:67]
	v_mfma_f32_16x16x32_bf16 v[68:71], v[156:159], v[208:211], v[68:71]
	s_setprio 0
	s_add_i32 s24, s54, s35
	v_lshl_add_u64 v[212:213], v[212:213], 0, s[16:17]
	s_mov_b32 m0, s24
	ds_read_b128 v[160:163], v199 offset:49152
	ds_read_b128 v[180:183], v199 offset:50176
	ds_read_b128 v[184:187], v199 offset:51200
	ds_read_b128 v[188:191], v199 offset:52224
	ds_read_b128 v[192:195], v199 offset:53248
	ds_read_b128 v[200:203], v199 offset:54272
	ds_read_b128 v[204:207], v199 offset:55296
	ds_read_b128 v[208:211], v199 offset:56320
	global_load_lds_dwordx4 v[212:213], off
	s_add_i32 m0, s24, 0x2000
	s_add_u32 s24, s26, 0xb0080
	v_lshl_add_u64 v[212:213], v[214:215], 0, s[16:17]
	s_addc_u32 s25, s27, 0
	s_add_i32 s26, s55, s35
	global_load_lds_dwordx4 v[212:213], off
	v_lshl_add_u64 v[212:213], s[24:25], 0, v[166:167]
	s_mov_b32 m0, s26
	s_nop 0
	global_load_lds_dwordx4 v[212:213], off
	v_lshl_add_u64 v[212:213], s[24:25], 0, v[170:171]
	s_add_i32 m0, s26, 0x2000
	s_nop 0
	global_load_lds_dwordx4 v[212:213], off
	v_lshl_add_u64 v[212:213], v[216:217], 0, s[16:17]
	s_mov_b32 m0, s41
	s_nop 0
	global_load_lds_dwordx4 v[212:213], off
	v_lshl_add_u64 v[212:213], v[218:219], 0, s[16:17]
	s_mov_b32 m0, s42
	s_nop 0
	global_load_lds_dwordx4 v[212:213], off
	s_waitcnt vmcnt(8)
	s_waitcnt lgkmcnt(0)
	s_barrier
	s_setprio 1
	s_waitcnt lgkmcnt(0)
	v_mfma_f32_16x16x32_bf16 v[56:59], v[128:131], v[160:163], v[56:59]
	v_mfma_f32_16x16x32_bf16 v[60:63], v[136:139], v[160:163], v[60:63]
	v_mfma_f32_16x16x32_bf16 v[40:43], v[128:131], v[184:187], v[40:43]
	v_mfma_f32_16x16x32_bf16 v[44:47], v[136:139], v[184:187], v[44:47]
	v_mfma_f32_16x16x32_bf16 v[24:27], v[128:131], v[192:195], v[24:27]
	v_mfma_f32_16x16x32_bf16 v[28:31], v[136:139], v[192:195], v[28:31]
	v_mfma_f32_16x16x32_bf16 v[8:11], v[128:131], v[204:207], v[8:11]
	v_mfma_f32_16x16x32_bf16 v[12:15], v[136:139], v[204:207], v[12:15]
	v_mfma_f32_16x16x32_bf16 v[56:59], v[132:135], v[180:183], v[56:59]
	v_mfma_f32_16x16x32_bf16 v[60:63], v[140:143], v[180:183], v[60:63]
	v_mfma_f32_16x16x32_bf16 v[40:43], v[132:135], v[188:191], v[40:43]
	v_mfma_f32_16x16x32_bf16 v[44:47], v[140:143], v[188:191], v[44:47]
	v_mfma_f32_16x16x32_bf16 v[24:27], v[132:135], v[200:203], v[24:27]
	v_mfma_f32_16x16x32_bf16 v[28:31], v[140:143], v[200:203], v[28:31]
	v_mfma_f32_16x16x32_bf16 v[8:11], v[132:135], v[208:211], v[8:11]
	v_mfma_f32_16x16x32_bf16 v[12:15], v[140:143], v[208:211], v[12:15]
	s_setprio 0
	s_setprio 1
	v_mfma_f32_16x16x32_bf16 v[48:51], v[144:147], v[160:163], v[48:51]
	v_mfma_f32_16x16x32_bf16 v[52:55], v[152:155], v[160:163], v[52:55]
	v_mfma_f32_16x16x32_bf16 v[32:35], v[144:147], v[184:187], v[32:35]
	v_mfma_f32_16x16x32_bf16 v[36:39], v[152:155], v[184:187], v[36:39]
	v_mfma_f32_16x16x32_bf16 v[16:19], v[144:147], v[192:195], v[16:19]
	v_mfma_f32_16x16x32_bf16 v[20:23], v[152:155], v[192:195], v[20:23]
	v_mfma_f32_16x16x32_bf16 v[0:3], v[144:147], v[204:207], v[0:3]
	v_mfma_f32_16x16x32_bf16 v[4:7], v[152:155], v[204:207], v[4:7]
	v_mfma_f32_16x16x32_bf16 v[48:51], v[148:151], v[180:183], v[48:51]
	v_mfma_f32_16x16x32_bf16 v[52:55], v[156:159], v[180:183], v[52:55]
	v_mfma_f32_16x16x32_bf16 v[32:35], v[148:151], v[188:191], v[32:35]
	v_mfma_f32_16x16x32_bf16 v[36:39], v[156:159], v[188:191], v[36:39]
	s_setprio 2
	s_barrier
	v_mfma_f32_16x16x32_bf16 v[16:19], v[148:151], v[200:203], v[16:19]
	v_mfma_f32_16x16x32_bf16 v[20:23], v[156:159], v[200:203], v[20:23]
	v_mfma_f32_16x16x32_bf16 v[0:3], v[148:151], v[208:211], v[0:3]
	v_mfma_f32_16x16x32_bf16 v[4:7], v[156:159], v[208:211], v[4:7]
	s_setprio 0
	s_add_i32 s53, s53, 2
	s_add_u32 s51, s51, 0x100
	s_addc_u32 s52, s52, 0
	s_cmp_gt_u32 s53, 41
	s_mov_b64 s[24:25], s[4:5]
	s_cbranch_scc0 .LBB0_1310
	s_and_b64 vcc, exec, s[18:19]
	s_cbranch_vccz .LBB0_1313
	s_barrier
